# sample-path GEMM cores (GLU, MLP-in, O-proj) rewritten by hand: coalesced quad loads + ds_bpermute lane transposition; f32 activations converted to bf16 at the same point as before
# speedup vs baseline: 1.0954x; 1.0216x over previous
.LBB0_369:
	s_and_b32 s14, s13, 0x60
	s_or_b32 s14, s14, s9
	s_and_b32 s15, s12, 0xffffff00
	s_and_b32 s16, s11, 0x70
	s_or_b32 s22, s15, s16
	s_add_i32 s23, s22, 0x80
	v_readfirstlane_b32 s18, v26
	v_readfirstlane_b32 s19, v27
	v_readfirstlane_b32 s20, v28
	v_readfirstlane_b32 s21, v29
	v_and_b32_e32 v238, 63, v0
	v_lshrrev_b32_e32 v236, 2, v238
	v_and_b32_e32 v226, 3, v238
	v_add_u32_e32 v228, s22, v236
	v_lshlrev_b32_e32 v228, 11, v228
	v_lshl_add_u32 v228, v226, 4, v228
	v_add_u32_e32 v232, s23, v236
	v_lshlrev_b32_e32 v232, 11, v232
	v_lshl_add_u32 v232, v226, 4, v232
	v_add_u32_e32 v238, s14, v236
	v_lshlrev_b32_e32 v238, 12, v238
	v_lshl_add_u32 v226, v226, 5, v238
	v_and_b32_e32 v238, 63, v0
	v_and_b32_e32 v236, 15, v238
	v_lshrrev_b32_e32 v238, 4, v238
	v_lshl_add_u32 v236, v236, 2, v238
	v_lshlrev_b32_e32 v236, 2, v236
	v_mov_b32_e32 v14, 0
	global_load_dwordx4 v[16:19], v226, s[18:19]
	global_load_dwordx4 v[20:23], v226, s[18:19] offset:16
	global_load_dwordx4 v[34:37], v228, s[20:21]
	global_load_dwordx4 v[38:41], v232, s[20:21]
	global_load_dwordx4 v[42:45], v226, s[18:19] offset:128
	global_load_dwordx4 v[46:49], v226, s[18:19] offset:144
	global_load_dwordx4 v[50:53], v228, s[20:21] offset:64
	global_load_dwordx4 v[54:57], v232, s[20:21] offset:64
	global_load_dwordx4 v[58:61], v226, s[18:19] offset:256
	global_load_dwordx4 v[62:65], v226, s[18:19] offset:272
	global_load_dwordx4 v[66:69], v228, s[20:21] offset:128
	global_load_dwordx4 v[70:73], v232, s[20:21] offset:128
	global_load_dwordx4 v[74:77], v226, s[18:19] offset:384
	global_load_dwordx4 v[78:81], v226, s[18:19] offset:400
	global_load_dwordx4 v[82:85], v228, s[20:21] offset:192
	global_load_dwordx4 v[86:89], v232, s[20:21] offset:192
	global_load_dwordx4 v[90:93], v226, s[18:19] offset:512
	global_load_dwordx4 v[94:97], v226, s[18:19] offset:528
	global_load_dwordx4 v[98:101], v228, s[20:21] offset:256
	global_load_dwordx4 v[102:105], v232, s[20:21] offset:256
	global_load_dwordx4 v[106:109], v226, s[18:19] offset:640
	global_load_dwordx4 v[110:113], v226, s[18:19] offset:656
	global_load_dwordx4 v[114:117], v228, s[20:21] offset:320
	global_load_dwordx4 v[118:121], v232, s[20:21] offset:320
	global_load_dwordx4 v[122:125], v226, s[18:19] offset:768
	global_load_dwordx4 v[126:129], v226, s[18:19] offset:784
	global_load_dwordx4 v[130:133], v228, s[20:21] offset:384
	global_load_dwordx4 v[134:137], v232, s[20:21] offset:384
	global_load_dwordx4 v[138:141], v226, s[18:19] offset:896
	global_load_dwordx4 v[142:145], v226, s[18:19] offset:912
	global_load_dwordx4 v[146:149], v228, s[20:21] offset:448
	global_load_dwordx4 v[150:153], v232, s[20:21] offset:448
	s_waitcnt vmcnt(28)
	ds_bpermute_b32 v188, v236, v16
	ds_bpermute_b32 v189, v236, v17
	ds_bpermute_b32 v190, v236, v18
	ds_bpermute_b32 v191, v236, v19
	ds_bpermute_b32 v192, v236, v20
	ds_bpermute_b32 v193, v236, v21
	ds_bpermute_b32 v194, v236, v22
	ds_bpermute_b32 v195, v236, v23
	ds_bpermute_b32 v196, v236, v34
	ds_bpermute_b32 v197, v236, v35
	ds_bpermute_b32 v198, v236, v36
	ds_bpermute_b32 v199, v236, v37
	ds_bpermute_b32 v200, v236, v38
	ds_bpermute_b32 v201, v236, v39
	ds_bpermute_b32 v202, v236, v40
	ds_bpermute_b32 v203, v236, v41
	s_waitcnt lgkmcnt(8)
	v_fmac_f32_e32 v14, v188, v188
	v_fmac_f32_e32 v14, v189, v189
	v_fmac_f32_e32 v14, v190, v190
	v_fmac_f32_e32 v14, v191, v191
	v_fmac_f32_e32 v14, v192, v192
	v_fmac_f32_e32 v14, v193, v193
	v_fmac_f32_e32 v14, v194, v194
	v_fmac_f32_e32 v14, v195, v195
	v_cvt_pk_bf16_f32 v188, v188, v189
	v_cvt_pk_bf16_f32 v189, v190, v191
	v_cvt_pk_bf16_f32 v190, v192, v193
	v_cvt_pk_bf16_f32 v191, v194, v195
	s_waitcnt vmcnt(24)
	ds_bpermute_b32 v204, v236, v42
	ds_bpermute_b32 v205, v236, v43
	ds_bpermute_b32 v206, v236, v44
	ds_bpermute_b32 v207, v236, v45
	ds_bpermute_b32 v208, v236, v46
	ds_bpermute_b32 v209, v236, v47
	ds_bpermute_b32 v210, v236, v48
	ds_bpermute_b32 v211, v236, v49
	s_waitcnt lgkmcnt(12)
	v_mfma_f32_16x16x32_bf16 v[2:5], v[188:191], v[196:199], 0
	ds_bpermute_b32 v212, v236, v50
	ds_bpermute_b32 v213, v236, v51
	ds_bpermute_b32 v214, v236, v52
	ds_bpermute_b32 v215, v236, v53
	s_waitcnt lgkmcnt(12)
	v_mfma_f32_16x16x32_bf16 v[6:9], v[188:191], v[200:203], 0
	ds_bpermute_b32 v216, v236, v54
	ds_bpermute_b32 v217, v236, v55
	ds_bpermute_b32 v218, v236, v56
	ds_bpermute_b32 v219, v236, v57
	s_waitcnt lgkmcnt(8)
	v_fmac_f32_e32 v14, v204, v204
	v_fmac_f32_e32 v14, v205, v205
	v_fmac_f32_e32 v14, v206, v206
	v_fmac_f32_e32 v14, v207, v207
	v_fmac_f32_e32 v14, v208, v208
	v_fmac_f32_e32 v14, v209, v209
	v_fmac_f32_e32 v14, v210, v210
	v_fmac_f32_e32 v14, v211, v211
	v_cvt_pk_bf16_f32 v204, v204, v205
	v_cvt_pk_bf16_f32 v205, v206, v207
	v_cvt_pk_bf16_f32 v206, v208, v209
	v_cvt_pk_bf16_f32 v207, v210, v211
	s_waitcnt vmcnt(20)
	ds_bpermute_b32 v188, v236, v58
	ds_bpermute_b32 v189, v236, v59
	ds_bpermute_b32 v190, v236, v60
	ds_bpermute_b32 v191, v236, v61
	ds_bpermute_b32 v192, v236, v62
	ds_bpermute_b32 v193, v236, v63
	ds_bpermute_b32 v194, v236, v64
	ds_bpermute_b32 v195, v236, v65
	s_waitcnt lgkmcnt(12)
	v_mfma_f32_16x16x32_bf16 v[2:5], v[204:207], v[212:215], v[2:5]
	ds_bpermute_b32 v196, v236, v66
	ds_bpermute_b32 v197, v236, v67
	ds_bpermute_b32 v198, v236, v68
	ds_bpermute_b32 v199, v236, v69
	s_waitcnt lgkmcnt(12)
	v_mfma_f32_16x16x32_bf16 v[6:9], v[204:207], v[216:219], v[6:9]
	ds_bpermute_b32 v200, v236, v70
	ds_bpermute_b32 v201, v236, v71
	ds_bpermute_b32 v202, v236, v72
	ds_bpermute_b32 v203, v236, v73
	s_waitcnt lgkmcnt(8)
	v_fmac_f32_e32 v14, v188, v188
	v_fmac_f32_e32 v14, v189, v189
	v_fmac_f32_e32 v14, v190, v190
	v_fmac_f32_e32 v14, v191, v191
	v_fmac_f32_e32 v14, v192, v192
	v_fmac_f32_e32 v14, v193, v193
	v_fmac_f32_e32 v14, v194, v194
	v_fmac_f32_e32 v14, v195, v195
	v_cvt_pk_bf16_f32 v188, v188, v189
	v_cvt_pk_bf16_f32 v189, v190, v191
	v_cvt_pk_bf16_f32 v190, v192, v193
	v_cvt_pk_bf16_f32 v191, v194, v195
	s_waitcnt vmcnt(16)
	ds_bpermute_b32 v204, v236, v74
	ds_bpermute_b32 v205, v236, v75
	ds_bpermute_b32 v206, v236, v76
	ds_bpermute_b32 v207, v236, v77
	ds_bpermute_b32 v208, v236, v78
	ds_bpermute_b32 v209, v236, v79
	ds_bpermute_b32 v210, v236, v80
	ds_bpermute_b32 v211, v236, v81
	s_waitcnt lgkmcnt(12)
	v_mfma_f32_16x16x32_bf16 v[2:5], v[188:191], v[196:199], v[2:5]
	ds_bpermute_b32 v212, v236, v82
	ds_bpermute_b32 v213, v236, v83
	ds_bpermute_b32 v214, v236, v84
	ds_bpermute_b32 v215, v236, v85
	s_waitcnt lgkmcnt(12)
	v_mfma_f32_16x16x32_bf16 v[6:9], v[188:191], v[200:203], v[6:9]
	ds_bpermute_b32 v216, v236, v86
	ds_bpermute_b32 v217, v236, v87
	ds_bpermute_b32 v218, v236, v88
	ds_bpermute_b32 v219, v236, v89
	s_waitcnt lgkmcnt(8)
	v_fmac_f32_e32 v14, v204, v204
	v_fmac_f32_e32 v14, v205, v205
	v_fmac_f32_e32 v14, v206, v206
	v_fmac_f32_e32 v14, v207, v207
	v_fmac_f32_e32 v14, v208, v208
	v_fmac_f32_e32 v14, v209, v209
	v_fmac_f32_e32 v14, v210, v210
	v_fmac_f32_e32 v14, v211, v211
	v_cvt_pk_bf16_f32 v204, v204, v205
	v_cvt_pk_bf16_f32 v205, v206, v207
	v_cvt_pk_bf16_f32 v206, v208, v209
	v_cvt_pk_bf16_f32 v207, v210, v211
	s_waitcnt vmcnt(12)
	ds_bpermute_b32 v188, v236, v90
	ds_bpermute_b32 v189, v236, v91
	ds_bpermute_b32 v190, v236, v92
	ds_bpermute_b32 v191, v236, v93
	ds_bpermute_b32 v192, v236, v94
	ds_bpermute_b32 v193, v236, v95
	ds_bpermute_b32 v194, v236, v96
	ds_bpermute_b32 v195, v236, v97
	s_waitcnt lgkmcnt(12)
	v_mfma_f32_16x16x32_bf16 v[2:5], v[204:207], v[212:215], v[2:5]
	ds_bpermute_b32 v196, v236, v98
	ds_bpermute_b32 v197, v236, v99
	ds_bpermute_b32 v198, v236, v100
	ds_bpermute_b32 v199, v236, v101
	s_waitcnt lgkmcnt(12)
	v_mfma_f32_16x16x32_bf16 v[6:9], v[204:207], v[216:219], v[6:9]
	ds_bpermute_b32 v200, v236, v102
	ds_bpermute_b32 v201, v236, v103
	ds_bpermute_b32 v202, v236, v104
	ds_bpermute_b32 v203, v236, v105
	s_waitcnt lgkmcnt(8)
	v_fmac_f32_e32 v14, v188, v188
	v_fmac_f32_e32 v14, v189, v189
	v_fmac_f32_e32 v14, v190, v190
	v_fmac_f32_e32 v14, v191, v191
	v_fmac_f32_e32 v14, v192, v192
	v_fmac_f32_e32 v14, v193, v193
	v_fmac_f32_e32 v14, v194, v194
	v_fmac_f32_e32 v14, v195, v195
	v_cvt_pk_bf16_f32 v188, v188, v189
	v_cvt_pk_bf16_f32 v189, v190, v191
	v_cvt_pk_bf16_f32 v190, v192, v193
	v_cvt_pk_bf16_f32 v191, v194, v195
	s_waitcnt vmcnt(8)
	ds_bpermute_b32 v204, v236, v106
	ds_bpermute_b32 v205, v236, v107
	ds_bpermute_b32 v206, v236, v108
	ds_bpermute_b32 v207, v236, v109
	ds_bpermute_b32 v208, v236, v110
	ds_bpermute_b32 v209, v236, v111
	ds_bpermute_b32 v210, v236, v112
	ds_bpermute_b32 v211, v236, v113
	s_waitcnt lgkmcnt(12)
	v_mfma_f32_16x16x32_bf16 v[2:5], v[188:191], v[196:199], v[2:5]
	ds_bpermute_b32 v212, v236, v114
	ds_bpermute_b32 v213, v236, v115
	ds_bpermute_b32 v214, v236, v116
	ds_bpermute_b32 v215, v236, v117
	s_waitcnt lgkmcnt(12)
	v_mfma_f32_16x16x32_bf16 v[6:9], v[188:191], v[200:203], v[6:9]
	ds_bpermute_b32 v216, v236, v118
	ds_bpermute_b32 v217, v236, v119
	ds_bpermute_b32 v218, v236, v120
	ds_bpermute_b32 v219, v236, v121
	s_waitcnt lgkmcnt(8)
	v_fmac_f32_e32 v14, v204, v204
	v_fmac_f32_e32 v14, v205, v205
	v_fmac_f32_e32 v14, v206, v206
	v_fmac_f32_e32 v14, v207, v207
	v_fmac_f32_e32 v14, v208, v208
	v_fmac_f32_e32 v14, v209, v209
	v_fmac_f32_e32 v14, v210, v210
	v_fmac_f32_e32 v14, v211, v211
	v_cvt_pk_bf16_f32 v204, v204, v205
	v_cvt_pk_bf16_f32 v205, v206, v207
	v_cvt_pk_bf16_f32 v206, v208, v209
	v_cvt_pk_bf16_f32 v207, v210, v211
	s_waitcnt vmcnt(4)
	ds_bpermute_b32 v188, v236, v122
	ds_bpermute_b32 v189, v236, v123
	ds_bpermute_b32 v190, v236, v124
	ds_bpermute_b32 v191, v236, v125
	ds_bpermute_b32 v192, v236, v126
	ds_bpermute_b32 v193, v236, v127
	ds_bpermute_b32 v194, v236, v128
	ds_bpermute_b32 v195, v236, v129
	s_waitcnt lgkmcnt(12)
	v_mfma_f32_16x16x32_bf16 v[2:5], v[204:207], v[212:215], v[2:5]
	ds_bpermute_b32 v196, v236, v130
	ds_bpermute_b32 v197, v236, v131
	ds_bpermute_b32 v198, v236, v132
	ds_bpermute_b32 v199, v236, v133
	s_waitcnt lgkmcnt(12)
	v_mfma_f32_16x16x32_bf16 v[6:9], v[204:207], v[216:219], v[6:9]
	ds_bpermute_b32 v200, v236, v134
	ds_bpermute_b32 v201, v236, v135
	ds_bpermute_b32 v202, v236, v136
	ds_bpermute_b32 v203, v236, v137
	s_waitcnt lgkmcnt(8)
	v_fmac_f32_e32 v14, v188, v188
	v_fmac_f32_e32 v14, v189, v189
	v_fmac_f32_e32 v14, v190, v190
	v_fmac_f32_e32 v14, v191, v191
	v_fmac_f32_e32 v14, v192, v192
	v_fmac_f32_e32 v14, v193, v193
	v_fmac_f32_e32 v14, v194, v194
	v_fmac_f32_e32 v14, v195, v195
	v_cvt_pk_bf16_f32 v188, v188, v189
	v_cvt_pk_bf16_f32 v189, v190, v191
	v_cvt_pk_bf16_f32 v190, v192, v193
	v_cvt_pk_bf16_f32 v191, v194, v195
	s_waitcnt vmcnt(0)
	ds_bpermute_b32 v204, v236, v138
	ds_bpermute_b32 v205, v236, v139
	ds_bpermute_b32 v206, v236, v140
	ds_bpermute_b32 v207, v236, v141
	ds_bpermute_b32 v208, v236, v142
	ds_bpermute_b32 v209, v236, v143
	ds_bpermute_b32 v210, v236, v144
	ds_bpermute_b32 v211, v236, v145
	s_waitcnt lgkmcnt(12)
	v_mfma_f32_16x16x32_bf16 v[2:5], v[188:191], v[196:199], v[2:5]
	ds_bpermute_b32 v212, v236, v146
	ds_bpermute_b32 v213, v236, v147
	ds_bpermute_b32 v214, v236, v148
	ds_bpermute_b32 v215, v236, v149
	s_waitcnt lgkmcnt(12)
	v_mfma_f32_16x16x32_bf16 v[6:9], v[188:191], v[200:203], v[6:9]
	ds_bpermute_b32 v216, v236, v150
	ds_bpermute_b32 v217, v236, v151
	ds_bpermute_b32 v218, v236, v152
	ds_bpermute_b32 v219, v236, v153
	s_waitcnt lgkmcnt(8)
	v_fmac_f32_e32 v14, v204, v204
	v_fmac_f32_e32 v14, v205, v205
	v_fmac_f32_e32 v14, v206, v206
	v_fmac_f32_e32 v14, v207, v207
	v_fmac_f32_e32 v14, v208, v208
	v_fmac_f32_e32 v14, v209, v209
	v_fmac_f32_e32 v14, v210, v210
	v_fmac_f32_e32 v14, v211, v211
	v_cvt_pk_bf16_f32 v204, v204, v205
	v_cvt_pk_bf16_f32 v205, v206, v207
	v_cvt_pk_bf16_f32 v206, v208, v209
	v_cvt_pk_bf16_f32 v207, v210, v211
	s_nop 1
	s_waitcnt lgkmcnt(4)
	v_mfma_f32_16x16x32_bf16 v[2:5], v[204:207], v[212:215], v[2:5]
	s_waitcnt lgkmcnt(0)
	v_mfma_f32_16x16x32_bf16 v[6:9], v[204:207], v[216:219], v[6:9]
	v_and_b32_e32 v240, 63, v0
	v_xor_b32_e32 v242, 32, v240
	v_xor_b32_e32 v240, 16, v240
	v_lshlrev_b32_e32 v240, 2, v240
	v_lshlrev_b32_e32 v242, 2, v242
	ds_bpermute_b32 v238, v240, v14
	s_waitcnt lgkmcnt(0)
	v_add_f32_e32 v14, v14, v238
	ds_bpermute_b32 v238, v242, v14
	s_waitcnt lgkmcnt(0)
	v_add_f32_e32 v14, v14, v238
	v_mov_b32_e32 v15, 0
	s_barrier
	s_nop 7
	ds_write_b128 v33, v[2:5]
	s_nop 1
	ds_write_b128 v33, v[6:9] offset:1024
	v_add_u32_e32 v2, s10, v30
	v_add_f32_e32 v10, v14, v15
	s_andn2_b64 vcc, exec, s[4:5]
	ds_write_b32 v2, v10 offset:32768
	s_waitcnt lgkmcnt(0)
	s_barrier
	s_cbranch_vccnz .LBB0_368
	v_and_or_b32 v2, s11, -16, v31
	v_ashrrev_i32_e32 v3, 31, v2
	v_lshlrev_b64 v[2:3], 2, v[2:3]
	v_lshl_add_u64 v[4:5], s[2:3], 0, v[2:3]
	global_load_dword v48, v[4:5], off
	v_add_co_u32_e32 v4, vcc, 0x1000, v4
	v_lshl_or_b32 v154, s14, 12, v32
	s_nop 0
	v_addc_co_u32_e32 v5, vcc, 0, v5, vcc
	global_load_dword v49, v[4:5], off
	v_lshl_add_u64 v[2:3], s[0:1], 0, v[2:3]
	v_lshl_add_u64 v[42:43], v[2:3], 0, v[154:155]
	v_add_co_u32_e32 v44, vcc, s96, v42
	s_nop 1
	v_addc_co_u32_e32 v45, vcc, 0, v43, vcc
	v_add_co_u32_e32 v46, vcc, 0x3000, v42
	s_nop 1
	v_addc_co_u32_e32 v47, vcc, 0, v43, vcc
	global_load_dword v50, v[42:43], off
	global_load_dword v51, v[44:45], off offset:-4096
	global_load_dword v52, v[44:45], off
	global_load_dword v53, v[46:47], off
	ds_read_b128 v[2:5], v33 offset:12288
	ds_read_b128 v[6:9], v33
	ds_read_b128 v[10:13], v33 offset:1024
	ds_read_b128 v[14:17], v33 offset:4096
	ds_read_b128 v[18:21], v33 offset:5120
	ds_read_b128 v[22:25], v33 offset:8192
	ds_read_b128 v[34:37], v33 offset:9216
	ds_read_b128 v[38:41], v33 offset:13312
	s_waitcnt lgkmcnt(4)
	v_add_f32_e32 v6, v6, v14
	s_waitcnt lgkmcnt(3)
	v_add_f32_e32 v10, v10, v18
	s_waitcnt lgkmcnt(2)
	v_add_f32_e32 v2, v22, v2
	v_add_f32_e32 v7, v7, v15
	s_waitcnt lgkmcnt(0)
	v_add_f32_e32 v14, v34, v38
	v_add_f32_e32 v3, v23, v3
	v_add_f32_e32 v11, v11, v19
	v_add_f32_e32 v15, v35, v39
	v_add_f32_e32 v8, v8, v16
	v_add_f32_e32 v4, v24, v4
	v_add_f32_e32 v12, v12, v20
	v_add_f32_e32 v16, v36, v40
	v_add_f32_e32 v9, v9, v17
	v_add_f32_e32 v5, v25, v5
	v_add_f32_e32 v13, v13, v21
	v_add_f32_e32 v17, v37, v41
	v_add_f32_e32 v2, v6, v2
	v_add_f32_e32 v6, v10, v14
	v_add_f32_e32 v3, v7, v3
	v_add_f32_e32 v7, v11, v15
	v_add_f32_e32 v4, v8, v4
	v_add_f32_e32 v8, v12, v16
	v_add_f32_e32 v5, v9, v5
	v_add_f32_e32 v9, v13, v17
	s_waitcnt vmcnt(5)
	v_add_f32_e32 v2, v2, v48
	v_add_f32_e32 v3, v3, v48
	v_add_f32_e32 v4, v4, v48
	v_add_f32_e32 v5, v5, v48
	s_waitcnt vmcnt(4)
	v_add_f32_e32 v6, v49, v6
	v_add_f32_e32 v7, v49, v7
	v_add_f32_e32 v8, v49, v8
	v_add_f32_e32 v9, v49, v9
	v_mul_f32_e32 v6, 0xbfb8aa3b, v6
	v_mul_f32_e32 v7, 0xbfb8aa3b, v7
	v_mul_f32_e32 v8, 0xbfb8aa3b, v8
	v_mul_f32_e32 v9, 0xbfb8aa3b, v9
	v_exp_f32_e32 v6, v6
	v_exp_f32_e32 v7, v7
	v_exp_f32_e32 v8, v8
	v_exp_f32_e32 v9, v9
	v_add_f32_e32 v6, 1.0, v6
	v_add_f32_e32 v7, 1.0, v7
	v_add_f32_e32 v8, 1.0, v8
	v_add_f32_e32 v9, 1.0, v9
	v_rcp_f32_e32 v6, v6
	v_rcp_f32_e32 v7, v7
	v_rcp_f32_e32 v8, v8
	v_rcp_f32_e32 v9, v9
	s_waitcnt vmcnt(3)
	v_fmac_f32_e32 v50, v2, v6
	s_waitcnt vmcnt(2)
	v_fmac_f32_e32 v51, v3, v7
	s_waitcnt vmcnt(1)
	v_fmac_f32_e32 v52, v4, v8
	s_waitcnt vmcnt(0)
	v_fmac_f32_e32 v53, v5, v9
	global_store_dword v[42:43], v50, off
	global_store_dword v[44:45], v51, off offset:-4096
	global_store_dword v[44:45], v52, off
	global_store_dword v[46:47], v53, off
	s_branch .LBB0_368

.LBB0_457:
	s_and_b32 s4, s9, 0xffffffc0
	s_and_b32 s5, s10, 0x60
	s_or_b32 s5, s5, s7
	v_readfirstlane_b32 s12, v70
	v_readfirstlane_b32 s13, v71
	v_readfirstlane_b32 s14, v74
	v_readfirstlane_b32 s15, v75
	s_mov_b32 s16, s4
	s_add_i32 s17, s4, 16
	s_add_i32 s18, s4, 32
	s_add_i32 s19, s4, 48
	v_and_b32_e32 v238, 63, v0
	v_lshrrev_b32_e32 v236, 2, v238
	v_and_b32_e32 v226, 3, v238
	v_add_u32_e32 v228, s16, v236
	v_lshlrev_b32_e32 v228, 11, v228
	v_lshl_add_u32 v228, v226, 4, v228
	v_add_u32_e32 v232, s17, v236
	v_lshlrev_b32_e32 v232, 11, v232
	v_lshl_add_u32 v232, v226, 4, v232
	v_add_u32_e32 v233, s18, v236
	v_lshlrev_b32_e32 v233, 11, v233
	v_lshl_add_u32 v233, v226, 4, v233
	v_add_u32_e32 v234, s19, v236
	v_lshlrev_b32_e32 v234, 11, v234
	v_lshl_add_u32 v234, v226, 4, v234
	v_add_u32_e32 v238, s5, v236
	v_lshlrev_b32_e32 v238, 12, v238
	v_lshl_add_u32 v226, v226, 5, v238
	v_and_b32_e32 v238, 63, v0
	v_and_b32_e32 v236, 15, v238
	v_lshrrev_b32_e32 v238, 4, v238
	v_lshl_add_u32 v236, v236, 2, v238
	v_lshlrev_b32_e32 v236, 2, v236
	v_mov_b32_e32 v22, 0
	global_load_dwordx4 v[24:27], v226, s[12:13]
	global_load_dwordx4 v[28:31], v226, s[12:13] offset:16
	global_load_dwordx4 v[32:35], v228, s[14:15]
	global_load_dwordx4 v[36:39], v232, s[14:15]
	global_load_dwordx4 v[40:43], v233, s[14:15]
	global_load_dwordx4 v[44:47], v234, s[14:15]
	global_load_dwordx4 v[48:51], v226, s[12:13] offset:128
	global_load_dwordx4 v[52:55], v226, s[12:13] offset:144
	global_load_dwordx4 v[56:59], v228, s[14:15] offset:64
	global_load_dwordx4 v[60:63], v232, s[14:15] offset:64
	global_load_dwordx4 v[64:67], v233, s[14:15] offset:64
	global_load_dwordx4 v[80:83], v234, s[14:15] offset:64
	global_load_dwordx4 v[84:87], v226, s[12:13] offset:256
	global_load_dwordx4 v[88:91], v226, s[12:13] offset:272
	global_load_dwordx4 v[92:95], v228, s[14:15] offset:128
	global_load_dwordx4 v[96:99], v232, s[14:15] offset:128
	global_load_dwordx4 v[100:103], v233, s[14:15] offset:128
	global_load_dwordx4 v[104:107], v234, s[14:15] offset:128
	global_load_dwordx4 v[108:111], v226, s[12:13] offset:384
	global_load_dwordx4 v[112:115], v226, s[12:13] offset:400
	global_load_dwordx4 v[116:119], v228, s[14:15] offset:192
	global_load_dwordx4 v[120:123], v232, s[14:15] offset:192
	global_load_dwordx4 v[124:127], v233, s[14:15] offset:192
	global_load_dwordx4 v[128:131], v234, s[14:15] offset:192
	global_load_dwordx4 v[132:135], v226, s[12:13] offset:512
	global_load_dwordx4 v[136:139], v226, s[12:13] offset:528
	global_load_dwordx4 v[140:143], v228, s[14:15] offset:256
	global_load_dwordx4 v[144:147], v232, s[14:15] offset:256
	global_load_dwordx4 v[148:151], v233, s[14:15] offset:256
	global_load_dwordx4 v[156:159], v234, s[14:15] offset:256
	s_waitcnt vmcnt(24)
	ds_bpermute_b32 v172, v236, v24
	ds_bpermute_b32 v173, v236, v25
	ds_bpermute_b32 v174, v236, v26
	ds_bpermute_b32 v175, v236, v27
	ds_bpermute_b32 v176, v236, v28
	ds_bpermute_b32 v177, v236, v29
	ds_bpermute_b32 v178, v236, v30
	ds_bpermute_b32 v179, v236, v31
	ds_bpermute_b32 v180, v236, v32
	ds_bpermute_b32 v181, v236, v33
	ds_bpermute_b32 v182, v236, v34
	ds_bpermute_b32 v183, v236, v35
	ds_bpermute_b32 v184, v236, v36
	ds_bpermute_b32 v185, v236, v37
	ds_bpermute_b32 v186, v236, v38
	ds_bpermute_b32 v187, v236, v39
	ds_bpermute_b32 v188, v236, v40
	ds_bpermute_b32 v189, v236, v41
	ds_bpermute_b32 v190, v236, v42
	ds_bpermute_b32 v191, v236, v43
	ds_bpermute_b32 v192, v236, v44
	ds_bpermute_b32 v193, v236, v45
	ds_bpermute_b32 v194, v236, v46
	ds_bpermute_b32 v195, v236, v47
	global_load_dwordx4 v[24:27], v226, s[12:13] offset:640
	global_load_dwordx4 v[28:31], v226, s[12:13] offset:656
	global_load_dwordx4 v[32:35], v228, s[14:15] offset:320
	global_load_dwordx4 v[36:39], v232, s[14:15] offset:320
	global_load_dwordx4 v[40:43], v233, s[14:15] offset:320
	global_load_dwordx4 v[44:47], v234, s[14:15] offset:320
	s_waitcnt lgkmcnt(15)
	v_fmac_f32_e32 v22, v172, v172
	v_fmac_f32_e32 v22, v173, v173
	v_fmac_f32_e32 v22, v174, v174
	v_fmac_f32_e32 v22, v175, v175
	v_fmac_f32_e32 v22, v176, v176
	v_fmac_f32_e32 v22, v177, v177
	v_fmac_f32_e32 v22, v178, v178
	v_fmac_f32_e32 v22, v179, v179
	v_cvt_pk_bf16_f32 v172, v172, v173
	v_cvt_pk_bf16_f32 v173, v174, v175
	v_cvt_pk_bf16_f32 v174, v176, v177
	v_cvt_pk_bf16_f32 v175, v178, v179
	s_waitcnt vmcnt(24)
	ds_bpermute_b32 v196, v236, v48
	ds_bpermute_b32 v197, v236, v49
	ds_bpermute_b32 v198, v236, v50
	ds_bpermute_b32 v199, v236, v51
	ds_bpermute_b32 v200, v236, v52
	ds_bpermute_b32 v201, v236, v53
	ds_bpermute_b32 v202, v236, v54
	ds_bpermute_b32 v203, v236, v55
	s_waitcnt lgkmcnt(15)
	v_mfma_f32_16x16x32_bf16 v[2:5], v[172:175], v[180:183], 0
	ds_bpermute_b32 v204, v236, v56
	ds_bpermute_b32 v205, v236, v57
	ds_bpermute_b32 v206, v236, v58
	ds_bpermute_b32 v207, v236, v59
	s_waitcnt lgkmcnt(15)
	v_mfma_f32_16x16x32_bf16 v[14:17], v[172:175], v[184:187], 0
	ds_bpermute_b32 v208, v236, v60
	ds_bpermute_b32 v209, v236, v61
	ds_bpermute_b32 v210, v236, v62
	ds_bpermute_b32 v211, v236, v63
	s_waitcnt lgkmcnt(15)
	v_mfma_f32_16x16x32_bf16 v[18:21], v[172:175], v[188:191], 0
	ds_bpermute_b32 v212, v236, v64
	ds_bpermute_b32 v213, v236, v65
	ds_bpermute_b32 v214, v236, v66
	ds_bpermute_b32 v215, v236, v67
	s_waitcnt lgkmcnt(15)
	v_mfma_f32_16x16x32_bf16 v[6:9], v[172:175], v[192:195], 0
	ds_bpermute_b32 v216, v236, v80
	ds_bpermute_b32 v217, v236, v81
	ds_bpermute_b32 v218, v236, v82
	ds_bpermute_b32 v219, v236, v83
	global_load_dwordx4 v[48:51], v226, s[12:13] offset:768
	global_load_dwordx4 v[52:55], v226, s[12:13] offset:784
	global_load_dwordx4 v[56:59], v228, s[14:15] offset:384
	global_load_dwordx4 v[60:63], v232, s[14:15] offset:384
	global_load_dwordx4 v[64:67], v233, s[14:15] offset:384
	global_load_dwordx4 v[80:83], v234, s[14:15] offset:384
	s_waitcnt lgkmcnt(15)
	v_fmac_f32_e32 v22, v196, v196
	v_fmac_f32_e32 v22, v197, v197
	v_fmac_f32_e32 v22, v198, v198
	v_fmac_f32_e32 v22, v199, v199
	v_fmac_f32_e32 v22, v200, v200
	v_fmac_f32_e32 v22, v201, v201
	v_fmac_f32_e32 v22, v202, v202
	v_fmac_f32_e32 v22, v203, v203
	v_cvt_pk_bf16_f32 v196, v196, v197
	v_cvt_pk_bf16_f32 v197, v198, v199
	v_cvt_pk_bf16_f32 v198, v200, v201
	v_cvt_pk_bf16_f32 v199, v202, v203
	s_waitcnt vmcnt(24)
	ds_bpermute_b32 v172, v236, v84
	ds_bpermute_b32 v173, v236, v85
	ds_bpermute_b32 v174, v236, v86
	ds_bpermute_b32 v175, v236, v87
	ds_bpermute_b32 v176, v236, v88
	ds_bpermute_b32 v177, v236, v89
	ds_bpermute_b32 v178, v236, v90
	ds_bpermute_b32 v179, v236, v91
	s_waitcnt lgkmcnt(15)
	v_mfma_f32_16x16x32_bf16 v[2:5], v[196:199], v[204:207], v[2:5]
	ds_bpermute_b32 v180, v236, v92
	ds_bpermute_b32 v181, v236, v93
	ds_bpermute_b32 v182, v236, v94
	ds_bpermute_b32 v183, v236, v95
	s_waitcnt lgkmcnt(15)
	v_mfma_f32_16x16x32_bf16 v[14:17], v[196:199], v[208:211], v[14:17]
	ds_bpermute_b32 v184, v236, v96
	ds_bpermute_b32 v185, v236, v97
	ds_bpermute_b32 v186, v236, v98
	ds_bpermute_b32 v187, v236, v99
	s_waitcnt lgkmcnt(15)
	v_mfma_f32_16x16x32_bf16 v[18:21], v[196:199], v[212:215], v[18:21]
	ds_bpermute_b32 v188, v236, v100
	ds_bpermute_b32 v189, v236, v101
	ds_bpermute_b32 v190, v236, v102
	ds_bpermute_b32 v191, v236, v103
	s_waitcnt lgkmcnt(15)
	v_mfma_f32_16x16x32_bf16 v[6:9], v[196:199], v[216:219], v[6:9]
	ds_bpermute_b32 v192, v236, v104
	ds_bpermute_b32 v193, v236, v105
	ds_bpermute_b32 v194, v236, v106
	ds_bpermute_b32 v195, v236, v107
	global_load_dwordx4 v[84:87], v226, s[12:13] offset:896
	global_load_dwordx4 v[88:91], v226, s[12:13] offset:912
	global_load_dwordx4 v[92:95], v228, s[14:15] offset:448
	global_load_dwordx4 v[96:99], v232, s[14:15] offset:448
	global_load_dwordx4 v[100:103], v233, s[14:15] offset:448
	global_load_dwordx4 v[104:107], v234, s[14:15] offset:448
	s_waitcnt lgkmcnt(15)
	v_fmac_f32_e32 v22, v172, v172
	v_fmac_f32_e32 v22, v173, v173
	v_fmac_f32_e32 v22, v174, v174
	v_fmac_f32_e32 v22, v175, v175
	v_fmac_f32_e32 v22, v176, v176
	v_fmac_f32_e32 v22, v177, v177
	v_fmac_f32_e32 v22, v178, v178
	v_fmac_f32_e32 v22, v179, v179
	v_cvt_pk_bf16_f32 v172, v172, v173
	v_cvt_pk_bf16_f32 v173, v174, v175
	v_cvt_pk_bf16_f32 v174, v176, v177
	v_cvt_pk_bf16_f32 v175, v178, v179
	s_waitcnt vmcnt(24)
	ds_bpermute_b32 v196, v236, v108
	ds_bpermute_b32 v197, v236, v109
	ds_bpermute_b32 v198, v236, v110
	ds_bpermute_b32 v199, v236, v111
	ds_bpermute_b32 v200, v236, v112
	ds_bpermute_b32 v201, v236, v113
	ds_bpermute_b32 v202, v236, v114
	ds_bpermute_b32 v203, v236, v115
	s_waitcnt lgkmcnt(15)
	v_mfma_f32_16x16x32_bf16 v[2:5], v[172:175], v[180:183], v[2:5]
	ds_bpermute_b32 v204, v236, v116
	ds_bpermute_b32 v205, v236, v117
	ds_bpermute_b32 v206, v236, v118
	ds_bpermute_b32 v207, v236, v119
	s_waitcnt lgkmcnt(15)
	v_mfma_f32_16x16x32_bf16 v[14:17], v[172:175], v[184:187], v[14:17]
	ds_bpermute_b32 v208, v236, v120
	ds_bpermute_b32 v209, v236, v121
	ds_bpermute_b32 v210, v236, v122
	ds_bpermute_b32 v211, v236, v123
	s_waitcnt lgkmcnt(15)
	v_mfma_f32_16x16x32_bf16 v[18:21], v[172:175], v[188:191], v[18:21]
	ds_bpermute_b32 v212, v236, v124
	ds_bpermute_b32 v213, v236, v125
	ds_bpermute_b32 v214, v236, v126
	ds_bpermute_b32 v215, v236, v127
	s_waitcnt lgkmcnt(15)
	v_mfma_f32_16x16x32_bf16 v[6:9], v[172:175], v[192:195], v[6:9]
	ds_bpermute_b32 v216, v236, v128
	ds_bpermute_b32 v217, v236, v129
	ds_bpermute_b32 v218, v236, v130
	ds_bpermute_b32 v219, v236, v131
	s_waitcnt lgkmcnt(15)
	v_fmac_f32_e32 v22, v196, v196
	v_fmac_f32_e32 v22, v197, v197
	v_fmac_f32_e32 v22, v198, v198
	v_fmac_f32_e32 v22, v199, v199
	v_fmac_f32_e32 v22, v200, v200
	v_fmac_f32_e32 v22, v201, v201
	v_fmac_f32_e32 v22, v202, v202
	v_fmac_f32_e32 v22, v203, v203
	v_cvt_pk_bf16_f32 v196, v196, v197
	v_cvt_pk_bf16_f32 v197, v198, v199
	v_cvt_pk_bf16_f32 v198, v200, v201
	v_cvt_pk_bf16_f32 v199, v202, v203
	s_waitcnt vmcnt(18)
	ds_bpermute_b32 v172, v236, v132
	ds_bpermute_b32 v173, v236, v133
	ds_bpermute_b32 v174, v236, v134
	ds_bpermute_b32 v175, v236, v135
	ds_bpermute_b32 v176, v236, v136
	ds_bpermute_b32 v177, v236, v137
	ds_bpermute_b32 v178, v236, v138
	ds_bpermute_b32 v179, v236, v139
	s_waitcnt lgkmcnt(15)
	v_mfma_f32_16x16x32_bf16 v[2:5], v[196:199], v[204:207], v[2:5]
	ds_bpermute_b32 v180, v236, v140
	ds_bpermute_b32 v181, v236, v141
	ds_bpermute_b32 v182, v236, v142
	ds_bpermute_b32 v183, v236, v143
	s_waitcnt lgkmcnt(15)
	v_mfma_f32_16x16x32_bf16 v[14:17], v[196:199], v[208:211], v[14:17]
	ds_bpermute_b32 v184, v236, v144
	ds_bpermute_b32 v185, v236, v145
	ds_bpermute_b32 v186, v236, v146
	ds_bpermute_b32 v187, v236, v147
	s_waitcnt lgkmcnt(15)
	v_mfma_f32_16x16x32_bf16 v[18:21], v[196:199], v[212:215], v[18:21]
	ds_bpermute_b32 v188, v236, v148
	ds_bpermute_b32 v189, v236, v149
	ds_bpermute_b32 v190, v236, v150
	ds_bpermute_b32 v191, v236, v151
	s_waitcnt lgkmcnt(15)
	v_mfma_f32_16x16x32_bf16 v[6:9], v[196:199], v[216:219], v[6:9]
	ds_bpermute_b32 v192, v236, v156
	ds_bpermute_b32 v193, v236, v157
	ds_bpermute_b32 v194, v236, v158
	ds_bpermute_b32 v195, v236, v159
	s_waitcnt lgkmcnt(15)
	v_fmac_f32_e32 v22, v172, v172
	v_fmac_f32_e32 v22, v173, v173
	v_fmac_f32_e32 v22, v174, v174
	v_fmac_f32_e32 v22, v175, v175
	v_fmac_f32_e32 v22, v176, v176
	v_fmac_f32_e32 v22, v177, v177
	v_fmac_f32_e32 v22, v178, v178
	v_fmac_f32_e32 v22, v179, v179
	v_cvt_pk_bf16_f32 v172, v172, v173
	v_cvt_pk_bf16_f32 v173, v174, v175
	v_cvt_pk_bf16_f32 v174, v176, v177
	v_cvt_pk_bf16_f32 v175, v178, v179
	s_waitcnt vmcnt(12)
	ds_bpermute_b32 v196, v236, v24
	ds_bpermute_b32 v197, v236, v25
	ds_bpermute_b32 v198, v236, v26
	ds_bpermute_b32 v199, v236, v27
	ds_bpermute_b32 v200, v236, v28
	ds_bpermute_b32 v201, v236, v29
	ds_bpermute_b32 v202, v236, v30
	ds_bpermute_b32 v203, v236, v31
	s_waitcnt lgkmcnt(15)
	v_mfma_f32_16x16x32_bf16 v[2:5], v[172:175], v[180:183], v[2:5]
	ds_bpermute_b32 v204, v236, v32
	ds_bpermute_b32 v205, v236, v33
	ds_bpermute_b32 v206, v236, v34
	ds_bpermute_b32 v207, v236, v35
	s_waitcnt lgkmcnt(15)
	v_mfma_f32_16x16x32_bf16 v[14:17], v[172:175], v[184:187], v[14:17]
	ds_bpermute_b32 v208, v236, v36
	ds_bpermute_b32 v209, v236, v37
	ds_bpermute_b32 v210, v236, v38
	ds_bpermute_b32 v211, v236, v39
	s_waitcnt lgkmcnt(15)
	v_mfma_f32_16x16x32_bf16 v[18:21], v[172:175], v[188:191], v[18:21]
	ds_bpermute_b32 v212, v236, v40
	ds_bpermute_b32 v213, v236, v41
	ds_bpermute_b32 v214, v236, v42
	ds_bpermute_b32 v215, v236, v43
	s_waitcnt lgkmcnt(15)
	v_mfma_f32_16x16x32_bf16 v[6:9], v[172:175], v[192:195], v[6:9]
	ds_bpermute_b32 v216, v236, v44
	ds_bpermute_b32 v217, v236, v45
	ds_bpermute_b32 v218, v236, v46
	ds_bpermute_b32 v219, v236, v47
	s_waitcnt lgkmcnt(15)
	v_fmac_f32_e32 v22, v196, v196
	v_fmac_f32_e32 v22, v197, v197
	v_fmac_f32_e32 v22, v198, v198
	v_fmac_f32_e32 v22, v199, v199
	v_fmac_f32_e32 v22, v200, v200
	v_fmac_f32_e32 v22, v201, v201
	v_fmac_f32_e32 v22, v202, v202
	v_fmac_f32_e32 v22, v203, v203
	v_cvt_pk_bf16_f32 v196, v196, v197
	v_cvt_pk_bf16_f32 v197, v198, v199
	v_cvt_pk_bf16_f32 v198, v200, v201
	v_cvt_pk_bf16_f32 v199, v202, v203
	s_waitcnt vmcnt(6)
	ds_bpermute_b32 v172, v236, v48
	ds_bpermute_b32 v173, v236, v49
	ds_bpermute_b32 v174, v236, v50
	ds_bpermute_b32 v175, v236, v51
	ds_bpermute_b32 v176, v236, v52
	ds_bpermute_b32 v177, v236, v53
	ds_bpermute_b32 v178, v236, v54
	ds_bpermute_b32 v179, v236, v55
	s_waitcnt lgkmcnt(15)
	v_mfma_f32_16x16x32_bf16 v[2:5], v[196:199], v[204:207], v[2:5]
	ds_bpermute_b32 v180, v236, v56
	ds_bpermute_b32 v181, v236, v57
	ds_bpermute_b32 v182, v236, v58
	ds_bpermute_b32 v183, v236, v59
	s_waitcnt lgkmcnt(15)
	v_mfma_f32_16x16x32_bf16 v[14:17], v[196:199], v[208:211], v[14:17]
	ds_bpermute_b32 v184, v236, v60
	ds_bpermute_b32 v185, v236, v61
	ds_bpermute_b32 v186, v236, v62
	ds_bpermute_b32 v187, v236, v63
	s_waitcnt lgkmcnt(15)
	v_mfma_f32_16x16x32_bf16 v[18:21], v[196:199], v[212:215], v[18:21]
	ds_bpermute_b32 v188, v236, v64
	ds_bpermute_b32 v189, v236, v65
	ds_bpermute_b32 v190, v236, v66
	ds_bpermute_b32 v191, v236, v67
	s_waitcnt lgkmcnt(15)
	v_mfma_f32_16x16x32_bf16 v[6:9], v[196:199], v[216:219], v[6:9]
	ds_bpermute_b32 v192, v236, v80
	ds_bpermute_b32 v193, v236, v81
	ds_bpermute_b32 v194, v236, v82
	ds_bpermute_b32 v195, v236, v83
	s_waitcnt lgkmcnt(15)
	v_fmac_f32_e32 v22, v172, v172
	v_fmac_f32_e32 v22, v173, v173
	v_fmac_f32_e32 v22, v174, v174
	v_fmac_f32_e32 v22, v175, v175
	v_fmac_f32_e32 v22, v176, v176
	v_fmac_f32_e32 v22, v177, v177
	v_fmac_f32_e32 v22, v178, v178
	v_fmac_f32_e32 v22, v179, v179
	v_cvt_pk_bf16_f32 v172, v172, v173
	v_cvt_pk_bf16_f32 v173, v174, v175
	v_cvt_pk_bf16_f32 v174, v176, v177
	v_cvt_pk_bf16_f32 v175, v178, v179
	s_waitcnt vmcnt(0)
	ds_bpermute_b32 v196, v236, v84
	ds_bpermute_b32 v197, v236, v85
	ds_bpermute_b32 v198, v236, v86
	ds_bpermute_b32 v199, v236, v87
	ds_bpermute_b32 v200, v236, v88
	ds_bpermute_b32 v201, v236, v89
	ds_bpermute_b32 v202, v236, v90
	ds_bpermute_b32 v203, v236, v91
	s_waitcnt lgkmcnt(15)
	v_mfma_f32_16x16x32_bf16 v[2:5], v[172:175], v[180:183], v[2:5]
	ds_bpermute_b32 v204, v236, v92
	ds_bpermute_b32 v205, v236, v93
	ds_bpermute_b32 v206, v236, v94
	ds_bpermute_b32 v207, v236, v95
	s_waitcnt lgkmcnt(15)
	v_mfma_f32_16x16x32_bf16 v[14:17], v[172:175], v[184:187], v[14:17]
	ds_bpermute_b32 v208, v236, v96
	ds_bpermute_b32 v209, v236, v97
	ds_bpermute_b32 v210, v236, v98
	ds_bpermute_b32 v211, v236, v99
	s_waitcnt lgkmcnt(15)
	v_mfma_f32_16x16x32_bf16 v[18:21], v[172:175], v[188:191], v[18:21]
	ds_bpermute_b32 v212, v236, v100
	ds_bpermute_b32 v213, v236, v101
	ds_bpermute_b32 v214, v236, v102
	ds_bpermute_b32 v215, v236, v103
	s_waitcnt lgkmcnt(15)
	v_mfma_f32_16x16x32_bf16 v[6:9], v[172:175], v[192:195], v[6:9]
	ds_bpermute_b32 v216, v236, v104
	ds_bpermute_b32 v217, v236, v105
	ds_bpermute_b32 v218, v236, v106
	ds_bpermute_b32 v219, v236, v107
	s_waitcnt lgkmcnt(15)
	v_fmac_f32_e32 v22, v196, v196
	v_fmac_f32_e32 v22, v197, v197
	v_fmac_f32_e32 v22, v198, v198
	v_fmac_f32_e32 v22, v199, v199
	v_fmac_f32_e32 v22, v200, v200
	v_fmac_f32_e32 v22, v201, v201
	v_fmac_f32_e32 v22, v202, v202
	v_fmac_f32_e32 v22, v203, v203
	v_cvt_pk_bf16_f32 v196, v196, v197
	v_cvt_pk_bf16_f32 v197, v198, v199
	v_cvt_pk_bf16_f32 v198, v200, v201
	v_cvt_pk_bf16_f32 v199, v202, v203
	s_nop 1
	s_waitcnt lgkmcnt(12)
	v_mfma_f32_16x16x32_bf16 v[2:5], v[196:199], v[204:207], v[2:5]
	s_waitcnt lgkmcnt(8)
	v_mfma_f32_16x16x32_bf16 v[14:17], v[196:199], v[208:211], v[14:17]
	s_waitcnt lgkmcnt(4)
	v_mfma_f32_16x16x32_bf16 v[18:21], v[196:199], v[212:215], v[18:21]
	s_waitcnt lgkmcnt(0)
	v_mfma_f32_16x16x32_bf16 v[6:9], v[196:199], v[216:219], v[6:9]
	v_and_b32_e32 v240, 63, v0
	v_xor_b32_e32 v242, 32, v240
	v_xor_b32_e32 v240, 16, v240
	v_lshlrev_b32_e32 v240, 2, v240
	v_lshlrev_b32_e32 v242, 2, v242
	ds_bpermute_b32 v238, v240, v22
	s_waitcnt lgkmcnt(0)
	v_add_f32_e32 v22, v22, v238
	ds_bpermute_b32 v238, v242, v22
	s_waitcnt lgkmcnt(0)
	v_add_f32_e32 v22, v22, v238
	v_mov_b32_e32 v23, 0
	s_barrier
	s_nop 7
	ds_write_b128 v79, v[2:5]
	ds_write_b128 v79, v[14:17] offset:1024
	ds_write_b128 v79, v[18:21] offset:2048
	s_nop 4
	ds_write_b128 v79, v[6:9] offset:3072
	v_add_u32_e32 v2, s8, v76
	s_andn2_b64 vcc, exec, s[0:1]
	s_waitcnt lgkmcnt(4)
	v_add_f32_e32 v10, v22, v23
	ds_write_b32 v2, v10 offset:32768
	s_waitcnt lgkmcnt(0)
	s_barrier
	s_cbranch_vccnz .LBB0_456
	ds_read_b128 v[4:7], v79
	ds_read_b128 v[8:11], v79 offset:8192
	ds_read_b128 v[12:15], v79 offset:16384
	ds_read_b128 v[16:19], v79 offset:24576
	ds_read_b128 v[20:23], v79 offset:1024
	ds_read_b128 v[24:27], v79 offset:9216
	s_waitcnt lgkmcnt(4)
	v_pk_add_f32 v[28:29], v[6:7], v[10:11]
	v_pk_add_f32 v[30:31], v[4:5], v[8:9]
	ds_read_b128 v[4:7], v79 offset:17408
	ds_read_b128 v[8:11], v79 offset:25600
	s_waitcnt lgkmcnt(4)
	v_pk_add_f32 v[14:15], v[14:15], v[18:19]
	v_pk_add_f32 v[12:13], v[12:13], v[16:17]
	v_pk_add_f32 v[28:29], v[28:29], v[14:15]
	v_pk_add_f32 v[30:31], v[30:31], v[12:13]
	s_waitcnt lgkmcnt(2)
	v_pk_add_f32 v[12:13], v[22:23], v[26:27]
	v_pk_add_f32 v[14:15], v[20:21], v[24:25]
	s_waitcnt lgkmcnt(0)
	v_pk_add_f32 v[6:7], v[6:7], v[10:11]
	v_pk_add_f32 v[4:5], v[4:5], v[8:9]
	v_pk_add_f32 v[32:33], v[12:13], v[6:7]
	v_pk_add_f32 v[34:35], v[14:15], v[4:5]
	ds_read_b128 v[4:7], v79 offset:2048
	ds_read_b128 v[8:11], v79 offset:10240
	ds_read_b128 v[12:15], v79 offset:18432
	ds_read_b128 v[16:19], v79 offset:26624
	ds_read_b128 v[20:23], v79 offset:3072
	ds_read_b128 v[24:27], v79 offset:11264
	s_waitcnt lgkmcnt(4)
	v_pk_add_f32 v[36:37], v[6:7], v[10:11]
	v_pk_add_f32 v[38:39], v[4:5], v[8:9]
	ds_read_b128 v[4:7], v79 offset:19456
	ds_read_b128 v[8:11], v79 offset:27648
	s_waitcnt lgkmcnt(4)
	v_pk_add_f32 v[12:13], v[12:13], v[16:17]
	ds_read2st64_b32 v[16:17], v2 offset0:128 offset1:130
	ds_read2st64_b32 v[2:3], v2 offset0:132 offset1:134
	v_pk_add_f32 v[14:15], v[14:15], v[18:19]
	s_waitcnt lgkmcnt(4)
	v_pk_add_f32 v[18:19], v[22:23], v[26:27]
	s_waitcnt lgkmcnt(2)
	v_pk_add_f32 v[6:7], v[6:7], v[10:11]
	s_waitcnt lgkmcnt(1)
	v_mov_b32_e32 v10, v16
	s_waitcnt lgkmcnt(0)
	v_mov_b32_e32 v11, v2
	v_mov_b32_e32 v2, v17
	v_pk_add_f32 v[2:3], v[10:11], v[2:3]
	v_pk_add_f32 v[20:21], v[20:21], v[24:25]
	v_add_f32_e32 v2, v2, v3
	v_fmamk_f32 v2, v2, 0x3a800000, v225
	v_mul_f32_e32 v3, 0x4b800000, v2
	v_cmp_gt_f32_e32 vcc, s90, v2
	v_pk_add_f32 v[12:13], v[38:39], v[12:13]
	v_pk_add_f32 v[14:15], v[36:37], v[14:15]
	v_cndmask_b32_e32 v2, v2, v3, vcc
	v_rsq_f32_e32 v10, v2
	v_pk_add_f32 v[2:3], v[4:5], v[8:9]
	v_pk_add_f32 v[4:5], v[18:19], v[6:7]
	v_and_or_b32 v7, v1, 64, v78
	v_mul_f32_e32 v6, 0x45800000, v10
	v_cndmask_b32_e32 v6, v10, v6, vcc
	v_lshlrev_b32_e32 v7, 2, v7
	ds_bpermute_b32 v8, v7, v6
	v_or_b32_e32 v9, s5, v78
	v_lshlrev_b32_e32 v154, 13, v9
	ds_bpermute_b32 v10, v7, v6 offset:4
	ds_bpermute_b32 v11, v7, v6 offset:8
	s_waitcnt lgkmcnt(2)
	v_mul_f32_e32 v9, v30, v8
	v_or_b32_e32 v7, 12, v7
	s_ashr_i32 s5, s4, 31
	v_max_f32_e32 v9, 0, v9
	ds_bpermute_b32 v16, v7, v6
	v_lshl_add_u64 v[6:7], s[4:5], 1, v[72:73]
	v_mul_f32_e32 v9, v9, v9
	v_lshl_add_u64 v[6:7], v[6:7], 0, v[154:155]
	v_cvt_pk_bf16_f32 v9, v9, v155
	global_store_short v[6:7], v9, off
	v_mul_f32_e32 v9, v34, v8
	v_max_f32_e32 v9, 0, v9
	v_mul_f32_e32 v9, v9, v9
	v_pk_add_f32 v[2:3], v[20:21], v[2:3]
	v_cvt_pk_bf16_f32 v9, v9, v155
	global_store_short v[6:7], v9, off offset:32
	v_mul_f32_e32 v9, v12, v8
	v_mul_f32_e32 v2, v2, v8
	v_max_f32_e32 v9, 0, v9
	v_max_f32_e32 v2, 0, v2
	v_mul_f32_e32 v9, v9, v9
	v_mul_f32_e32 v2, v2, v2
	v_cvt_pk_bf16_f32 v9, v9, v155
	global_store_short v[6:7], v9, off offset:64
	v_cvt_pk_bf16_f32 v2, v2, v155
	global_store_short v[6:7], v2, off offset:96
	s_waitcnt lgkmcnt(2)
	v_mul_f32_e32 v2, v31, v10
	v_max_f32_e32 v2, 0, v2
	v_mul_f32_e32 v2, v2, v2
	v_add_co_u32_e32 v8, vcc, s96, v6
	v_cvt_pk_bf16_f32 v2, v2, v155
	s_movk_i32 s4, 0x4000
	s_nop 0
	v_addc_co_u32_e32 v9, vcc, 0, v7, vcc
	global_store_short v[8:9], v2, off
	v_mul_f32_e32 v2, v35, v10
	v_max_f32_e32 v2, 0, v2
	v_mul_f32_e32 v2, v2, v2
	v_cvt_pk_bf16_f32 v2, v2, v155
	global_store_short v[8:9], v2, off offset:32
	v_mul_f32_e32 v2, v13, v10
	v_max_f32_e32 v2, 0, v2
	v_mul_f32_e32 v2, v2, v2
	v_cvt_pk_bf16_f32 v2, v2, v155
	global_store_short v[8:9], v2, off offset:64
	v_mul_f32_e32 v2, v3, v10
	v_max_f32_e32 v2, 0, v2
	v_mul_f32_e32 v2, v2, v2
	v_cvt_pk_bf16_f32 v2, v2, v155
	global_store_short v[8:9], v2, off offset:96
	s_waitcnt lgkmcnt(1)
	v_mul_f32_e32 v2, v28, v11
	v_max_f32_e32 v2, 0, v2
	v_mul_f32_e32 v2, v2, v2
	v_cvt_pk_bf16_f32 v8, v2, v155
	v_add_co_u32_e32 v2, vcc, s4, v6
	v_mul_f32_e32 v4, v4, v11
	s_nop 0
	v_addc_co_u32_e32 v3, vcc, 0, v7, vcc
	global_store_short v[2:3], v8, off
	v_mul_f32_e32 v8, v32, v11
	v_max_f32_e32 v8, 0, v8
	v_mul_f32_e32 v8, v8, v8
	v_cvt_pk_bf16_f32 v8, v8, v155
	global_store_short v[2:3], v8, off offset:32
	v_mul_f32_e32 v8, v14, v11
	v_max_f32_e32 v8, 0, v8
	v_max_f32_e32 v4, 0, v4
	v_mul_f32_e32 v8, v8, v8
	v_mul_f32_e32 v4, v4, v4
	v_cvt_pk_bf16_f32 v8, v8, v155
	global_store_short v[2:3], v8, off offset:64
	v_cvt_pk_bf16_f32 v4, v4, v155
	global_store_short v[2:3], v4, off offset:96
	s_waitcnt lgkmcnt(0)
	v_mul_f32_e32 v2, v29, v16
	v_max_f32_e32 v2, 0, v2
	v_mul_f32_e32 v2, v2, v2
	s_movk_i32 s4, 0x6000
	v_cvt_pk_bf16_f32 v4, v2, v155
	v_add_co_u32_e32 v2, vcc, s4, v6
	s_nop 1
	v_addc_co_u32_e32 v3, vcc, 0, v7, vcc
	global_store_short v[2:3], v4, off
	v_mul_f32_e32 v4, v33, v16
	v_max_f32_e32 v4, 0, v4
	v_mul_f32_e32 v4, v4, v4
	v_cvt_pk_bf16_f32 v4, v4, v155
	global_store_short v[2:3], v4, off offset:32
	v_mul_f32_e32 v4, v15, v16
	v_max_f32_e32 v4, 0, v4
	v_mul_f32_e32 v4, v4, v4
	v_cvt_pk_bf16_f32 v4, v4, v155
	global_store_short v[2:3], v4, off offset:64
	v_mul_f32_e32 v4, v5, v16
	v_max_f32_e32 v4, 0, v4
	v_mul_f32_e32 v4, v4, v4
	v_cvt_pk_bf16_f32 v4, v4, v155
	global_store_short v[2:3], v4, off offset:96
	s_branch .LBB0_456

.LBB0_964:
	s_and_b32 s4, s10, 0x60
	s_or_b32 s11, s4, s7
	v_readfirstlane_b32 s12, v22
	v_readfirstlane_b32 s13, v23
	v_readfirstlane_b32 s14, v26
	v_readfirstlane_b32 s15, v27
	s_and_b32 s16, s9, -16
	v_and_b32_e32 v251, 63, v0
	v_lshrrev_b32_e32 v250, 2, v251
	v_and_b32_e32 v243, 3, v251
	v_add_u32_e32 v246, s16, v250
	v_lshlrev_b32_e32 v246, 11, v246
	v_lshl_add_u32 v246, v243, 4, v246
	v_add_u32_e32 v251, s11, v250
	v_lshlrev_b32_e32 v251, 12, v251
	v_lshl_add_u32 v243, v243, 5, v251
	v_and_b32_e32 v251, 63, v0
	v_and_b32_e32 v250, 15, v251
	v_lshrrev_b32_e32 v251, 4, v251
	v_lshl_add_u32 v250, v250, 2, v251
	v_lshlrev_b32_e32 v250, 2, v250
	v_mov_b32_e32 v6, 0
	global_load_dwordx4 v[32:35], v243, s[12:13]
	global_load_dwordx4 v[36:39], v243, s[12:13] offset:16
	global_load_dwordx4 v[40:43], v246, s[14:15]
	global_load_dwordx4 v[44:47], v243, s[12:13] offset:128
	global_load_dwordx4 v[48:51], v243, s[12:13] offset:144
	global_load_dwordx4 v[52:55], v246, s[14:15] offset:64
	global_load_dwordx4 v[56:59], v243, s[12:13] offset:256
	global_load_dwordx4 v[60:63], v243, s[12:13] offset:272
	global_load_dwordx4 v[64:67], v246, s[14:15] offset:128
	global_load_dwordx4 v[68:71], v243, s[12:13] offset:384
	global_load_dwordx4 v[72:75], v243, s[12:13] offset:400
	global_load_dwordx4 v[76:79], v246, s[14:15] offset:192
	global_load_dwordx4 v[80:83], v243, s[12:13] offset:512
	global_load_dwordx4 v[84:87], v243, s[12:13] offset:528
	global_load_dwordx4 v[88:91], v246, s[14:15] offset:256
	global_load_dwordx4 v[92:95], v243, s[12:13] offset:640
	global_load_dwordx4 v[96:99], v243, s[12:13] offset:656
	global_load_dwordx4 v[100:103], v246, s[14:15] offset:320
	global_load_dwordx4 v[104:107], v243, s[12:13] offset:768
	global_load_dwordx4 v[108:111], v243, s[12:13] offset:784
	global_load_dwordx4 v[112:115], v246, s[14:15] offset:384
	global_load_dwordx4 v[116:119], v243, s[12:13] offset:896
	global_load_dwordx4 v[120:123], v243, s[12:13] offset:912
	global_load_dwordx4 v[124:127], v246, s[14:15] offset:448
	s_waitcnt vmcnt(21)
	ds_bpermute_b32 v206, v250, v32
	ds_bpermute_b32 v207, v250, v33
	ds_bpermute_b32 v208, v250, v34
	ds_bpermute_b32 v209, v250, v35
	ds_bpermute_b32 v210, v250, v36
	ds_bpermute_b32 v211, v250, v37
	ds_bpermute_b32 v212, v250, v38
	ds_bpermute_b32 v213, v250, v39
	ds_bpermute_b32 v214, v250, v40
	ds_bpermute_b32 v215, v250, v41
	ds_bpermute_b32 v216, v250, v42
	ds_bpermute_b32 v217, v250, v43
	s_waitcnt lgkmcnt(4)
	v_fmac_f32_e32 v6, v206, v206
	v_fmac_f32_e32 v6, v207, v207
	v_fmac_f32_e32 v6, v208, v208
	v_fmac_f32_e32 v6, v209, v209
	v_fmac_f32_e32 v6, v210, v210
	v_fmac_f32_e32 v6, v211, v211
	v_fmac_f32_e32 v6, v212, v212
	v_fmac_f32_e32 v6, v213, v213
	v_cvt_pk_bf16_f32 v206, v206, v207
	v_cvt_pk_bf16_f32 v207, v208, v209
	v_cvt_pk_bf16_f32 v208, v210, v211
	v_cvt_pk_bf16_f32 v209, v212, v213
	s_waitcnt vmcnt(18)
	ds_bpermute_b32 v218, v250, v44
	ds_bpermute_b32 v219, v250, v45
	ds_bpermute_b32 v220, v250, v46
	ds_bpermute_b32 v221, v250, v47
	ds_bpermute_b32 v222, v250, v48
	ds_bpermute_b32 v223, v250, v49
	ds_bpermute_b32 v224, v250, v50
	ds_bpermute_b32 v225, v250, v51
	s_waitcnt lgkmcnt(8)
	v_mfma_f32_16x16x32_bf16 v[2:5], v[206:209], v[214:217], 0
	ds_bpermute_b32 v226, v250, v52
	ds_bpermute_b32 v227, v250, v53
	ds_bpermute_b32 v228, v250, v54
	ds_bpermute_b32 v229, v250, v55
	s_waitcnt lgkmcnt(4)
	v_fmac_f32_e32 v6, v218, v218
	v_fmac_f32_e32 v6, v219, v219
	v_fmac_f32_e32 v6, v220, v220
	v_fmac_f32_e32 v6, v221, v221
	v_fmac_f32_e32 v6, v222, v222
	v_fmac_f32_e32 v6, v223, v223
	v_fmac_f32_e32 v6, v224, v224
	v_fmac_f32_e32 v6, v225, v225
	v_cvt_pk_bf16_f32 v218, v218, v219
	v_cvt_pk_bf16_f32 v219, v220, v221
	v_cvt_pk_bf16_f32 v220, v222, v223
	v_cvt_pk_bf16_f32 v221, v224, v225
	s_waitcnt vmcnt(15)
	ds_bpermute_b32 v206, v250, v56
	ds_bpermute_b32 v207, v250, v57
	ds_bpermute_b32 v208, v250, v58
	ds_bpermute_b32 v209, v250, v59
	ds_bpermute_b32 v210, v250, v60
	ds_bpermute_b32 v211, v250, v61
	ds_bpermute_b32 v212, v250, v62
	ds_bpermute_b32 v213, v250, v63
	s_waitcnt lgkmcnt(8)
	v_mfma_f32_16x16x32_bf16 v[2:5], v[218:221], v[226:229], v[2:5]
	ds_bpermute_b32 v214, v250, v64
	ds_bpermute_b32 v215, v250, v65
	ds_bpermute_b32 v216, v250, v66
	ds_bpermute_b32 v217, v250, v67
	s_waitcnt lgkmcnt(4)
	v_fmac_f32_e32 v6, v206, v206
	v_fmac_f32_e32 v6, v207, v207
	v_fmac_f32_e32 v6, v208, v208
	v_fmac_f32_e32 v6, v209, v209
	v_fmac_f32_e32 v6, v210, v210
	v_fmac_f32_e32 v6, v211, v211
	v_fmac_f32_e32 v6, v212, v212
	v_fmac_f32_e32 v6, v213, v213
	v_cvt_pk_bf16_f32 v206, v206, v207
	v_cvt_pk_bf16_f32 v207, v208, v209
	v_cvt_pk_bf16_f32 v208, v210, v211
	v_cvt_pk_bf16_f32 v209, v212, v213
	s_waitcnt vmcnt(12)
	ds_bpermute_b32 v218, v250, v68
	ds_bpermute_b32 v219, v250, v69
	ds_bpermute_b32 v220, v250, v70
	ds_bpermute_b32 v221, v250, v71
	ds_bpermute_b32 v222, v250, v72
	ds_bpermute_b32 v223, v250, v73
	ds_bpermute_b32 v224, v250, v74
	ds_bpermute_b32 v225, v250, v75
	s_waitcnt lgkmcnt(8)
	v_mfma_f32_16x16x32_bf16 v[2:5], v[206:209], v[214:217], v[2:5]
	ds_bpermute_b32 v226, v250, v76
	ds_bpermute_b32 v227, v250, v77
	ds_bpermute_b32 v228, v250, v78
	ds_bpermute_b32 v229, v250, v79
	s_waitcnt lgkmcnt(4)
	v_fmac_f32_e32 v6, v218, v218
	v_fmac_f32_e32 v6, v219, v219
	v_fmac_f32_e32 v6, v220, v220
	v_fmac_f32_e32 v6, v221, v221
	v_fmac_f32_e32 v6, v222, v222
	v_fmac_f32_e32 v6, v223, v223
	v_fmac_f32_e32 v6, v224, v224
	v_fmac_f32_e32 v6, v225, v225
	v_cvt_pk_bf16_f32 v218, v218, v219
	v_cvt_pk_bf16_f32 v219, v220, v221
	v_cvt_pk_bf16_f32 v220, v222, v223
	v_cvt_pk_bf16_f32 v221, v224, v225
	s_waitcnt vmcnt(9)
	ds_bpermute_b32 v206, v250, v80
	ds_bpermute_b32 v207, v250, v81
	ds_bpermute_b32 v208, v250, v82
	ds_bpermute_b32 v209, v250, v83
	ds_bpermute_b32 v210, v250, v84
	ds_bpermute_b32 v211, v250, v85
	ds_bpermute_b32 v212, v250, v86
	ds_bpermute_b32 v213, v250, v87
	s_waitcnt lgkmcnt(8)
	v_mfma_f32_16x16x32_bf16 v[2:5], v[218:221], v[226:229], v[2:5]
	ds_bpermute_b32 v214, v250, v88
	ds_bpermute_b32 v215, v250, v89
	ds_bpermute_b32 v216, v250, v90
	ds_bpermute_b32 v217, v250, v91
	s_waitcnt lgkmcnt(4)
	v_fmac_f32_e32 v6, v206, v206
	v_fmac_f32_e32 v6, v207, v207
	v_fmac_f32_e32 v6, v208, v208
	v_fmac_f32_e32 v6, v209, v209
	v_fmac_f32_e32 v6, v210, v210
	v_fmac_f32_e32 v6, v211, v211
	v_fmac_f32_e32 v6, v212, v212
	v_fmac_f32_e32 v6, v213, v213
	v_cvt_pk_bf16_f32 v206, v206, v207
	v_cvt_pk_bf16_f32 v207, v208, v209
	v_cvt_pk_bf16_f32 v208, v210, v211
	v_cvt_pk_bf16_f32 v209, v212, v213
	s_waitcnt vmcnt(6)
	ds_bpermute_b32 v218, v250, v92
	ds_bpermute_b32 v219, v250, v93
	ds_bpermute_b32 v220, v250, v94
	ds_bpermute_b32 v221, v250, v95
	ds_bpermute_b32 v222, v250, v96
	ds_bpermute_b32 v223, v250, v97
	ds_bpermute_b32 v224, v250, v98
	ds_bpermute_b32 v225, v250, v99
	s_waitcnt lgkmcnt(8)
	v_mfma_f32_16x16x32_bf16 v[2:5], v[206:209], v[214:217], v[2:5]
	ds_bpermute_b32 v226, v250, v100
	ds_bpermute_b32 v227, v250, v101
	ds_bpermute_b32 v228, v250, v102
	ds_bpermute_b32 v229, v250, v103
	s_waitcnt lgkmcnt(4)
	v_fmac_f32_e32 v6, v218, v218
	v_fmac_f32_e32 v6, v219, v219
	v_fmac_f32_e32 v6, v220, v220
	v_fmac_f32_e32 v6, v221, v221
	v_fmac_f32_e32 v6, v222, v222
	v_fmac_f32_e32 v6, v223, v223
	v_fmac_f32_e32 v6, v224, v224
	v_fmac_f32_e32 v6, v225, v225
	v_cvt_pk_bf16_f32 v218, v218, v219
	v_cvt_pk_bf16_f32 v219, v220, v221
	v_cvt_pk_bf16_f32 v220, v222, v223
	v_cvt_pk_bf16_f32 v221, v224, v225
	s_waitcnt vmcnt(3)
	ds_bpermute_b32 v206, v250, v104
	ds_bpermute_b32 v207, v250, v105
	ds_bpermute_b32 v208, v250, v106
	ds_bpermute_b32 v209, v250, v107
	ds_bpermute_b32 v210, v250, v108
	ds_bpermute_b32 v211, v250, v109
	ds_bpermute_b32 v212, v250, v110
	ds_bpermute_b32 v213, v250, v111
	s_waitcnt lgkmcnt(8)
	v_mfma_f32_16x16x32_bf16 v[2:5], v[218:221], v[226:229], v[2:5]
	ds_bpermute_b32 v214, v250, v112
	ds_bpermute_b32 v215, v250, v113
	ds_bpermute_b32 v216, v250, v114
	ds_bpermute_b32 v217, v250, v115
	s_waitcnt lgkmcnt(4)
	v_fmac_f32_e32 v6, v206, v206
	v_fmac_f32_e32 v6, v207, v207
	v_fmac_f32_e32 v6, v208, v208
	v_fmac_f32_e32 v6, v209, v209
	v_fmac_f32_e32 v6, v210, v210
	v_fmac_f32_e32 v6, v211, v211
	v_fmac_f32_e32 v6, v212, v212
	v_fmac_f32_e32 v6, v213, v213
	v_cvt_pk_bf16_f32 v206, v206, v207
	v_cvt_pk_bf16_f32 v207, v208, v209
	v_cvt_pk_bf16_f32 v208, v210, v211
	v_cvt_pk_bf16_f32 v209, v212, v213
	s_waitcnt vmcnt(0)
	ds_bpermute_b32 v218, v250, v116
	ds_bpermute_b32 v219, v250, v117
	ds_bpermute_b32 v220, v250, v118
	ds_bpermute_b32 v221, v250, v119
	ds_bpermute_b32 v222, v250, v120
	ds_bpermute_b32 v223, v250, v121
	ds_bpermute_b32 v224, v250, v122
	ds_bpermute_b32 v225, v250, v123
	s_waitcnt lgkmcnt(8)
	v_mfma_f32_16x16x32_bf16 v[2:5], v[206:209], v[214:217], v[2:5]
	ds_bpermute_b32 v226, v250, v124
	ds_bpermute_b32 v227, v250, v125
	ds_bpermute_b32 v228, v250, v126
	ds_bpermute_b32 v229, v250, v127
	s_waitcnt lgkmcnt(4)
	v_fmac_f32_e32 v6, v218, v218
	v_fmac_f32_e32 v6, v219, v219
	v_fmac_f32_e32 v6, v220, v220
	v_fmac_f32_e32 v6, v221, v221
	v_fmac_f32_e32 v6, v222, v222
	v_fmac_f32_e32 v6, v223, v223
	v_fmac_f32_e32 v6, v224, v224
	v_fmac_f32_e32 v6, v225, v225
	v_cvt_pk_bf16_f32 v218, v218, v219
	v_cvt_pk_bf16_f32 v219, v220, v221
	v_cvt_pk_bf16_f32 v220, v222, v223
	v_cvt_pk_bf16_f32 v221, v224, v225
	s_nop 1
	s_waitcnt lgkmcnt(0)
	v_mfma_f32_16x16x32_bf16 v[2:5], v[218:221], v[226:229], v[2:5]
	v_and_b32_e32 v252, 63, v0
	v_xor_b32_e32 v254, 32, v252
	v_xor_b32_e32 v252, 16, v252
	v_lshlrev_b32_e32 v252, 2, v252
	v_lshlrev_b32_e32 v254, 2, v254
	ds_bpermute_b32 v251, v252, v6
	s_waitcnt lgkmcnt(0)
	v_add_f32_e32 v6, v6, v251
	ds_bpermute_b32 v251, v254, v6
	s_waitcnt lgkmcnt(0)
	v_add_f32_e32 v6, v6, v251
	s_and_b32 s4, s9, -16
	s_barrier
	s_andn2_b64 vcc, exec, s[0:1]
	s_nop 7
	ds_write_b128 v31, v[2:5]
	v_add_u32_e32 v2, s8, v28
	ds_write_b32 v2, v6 offset:32768
	s_waitcnt lgkmcnt(0)
	s_barrier
	s_cbranch_vccnz .LBB0_963
	s_ashr_i32 s5, s4, 31
	v_lshl_add_u64 v[2:3], s[4:5], 2, v[24:25]
	v_lshl_or_b32 v194, s11, 12, v30
	v_lshl_add_u64 v[18:19], v[2:3], 0, v[194:195]
	s_movk_i32 s4, 0x2000
	v_add_co_u32_e32 v20, vcc, s4, v18
	s_nop 1
	v_addc_co_u32_e32 v21, vcc, 0, v19, vcc
	v_add_co_u32_e32 v32, vcc, 0x3000, v18
	global_load_dword v34, v[18:19], off
	global_load_dword v35, v[20:21], off offset:-4096
	global_load_dword v36, v[20:21], off
	v_addc_co_u32_e32 v33, vcc, 0, v19, vcc
	global_load_dword v37, v[32:33], off
	ds_read_b128 v[2:5], v31
	ds_read_b128 v[6:9], v31 offset:2048
	ds_read_b128 v[10:13], v31 offset:4096
	ds_read_b128 v[14:17], v31 offset:6144
	s_waitcnt lgkmcnt(2)
	v_add_f32_e32 v2, v2, v6
	v_add_f32_e32 v3, v3, v7
	s_waitcnt lgkmcnt(0)
	v_add_f32_e32 v6, v10, v14
	v_add_f32_e32 v7, v11, v15
	v_add_f32_e32 v2, v2, v6
	v_add_f32_e32 v4, v4, v8
	v_add_f32_e32 v8, v12, v16
	v_add_f32_e32 v5, v5, v9
	v_add_f32_e32 v9, v13, v17
	v_add_f32_e32 v3, v3, v7
	v_add_f32_e32 v4, v4, v8
	v_add_f32_e32 v5, v5, v9
	s_waitcnt vmcnt(3)
	v_add_f32_e32 v2, v34, v2
	global_store_dword v[18:19], v2, off
	s_waitcnt vmcnt(3)
	v_add_f32_e32 v2, v3, v35
	s_waitcnt vmcnt(2)
	v_add_f32_e32 v3, v4, v36
	global_store_dword v[20:21], v2, off offset:-4096
	global_store_dword v[20:21], v3, off
	s_waitcnt vmcnt(3)
	v_add_f32_e32 v2, v5, v37
	global_store_dword v[32:33], v2, off
	s_branch .LBB0_963

.LBB0_1052:
	s_and_b32 s4, s9, 0xffffffc0
	s_and_b32 s5, s10, 0x60
	s_or_b32 s5, s5, s7
	v_readfirstlane_b32 s12, v70
	v_readfirstlane_b32 s13, v71
	v_readfirstlane_b32 s14, v74
	v_readfirstlane_b32 s15, v75
	s_mov_b32 s16, s4
	s_add_i32 s17, s4, 16
	s_add_i32 s18, s4, 32
	s_add_i32 s19, s4, 48
	v_and_b32_e32 v251, 63, v0
	v_lshrrev_b32_e32 v250, 2, v251
	v_and_b32_e32 v243, 3, v251
	v_add_u32_e32 v246, s16, v250
	v_lshlrev_b32_e32 v246, 11, v246
	v_lshl_add_u32 v246, v243, 4, v246
	v_add_u32_e32 v247, s17, v250
	v_lshlrev_b32_e32 v247, 11, v247
	v_lshl_add_u32 v247, v243, 4, v247
	v_add_u32_e32 v248, s18, v250
	v_lshlrev_b32_e32 v248, 11, v248
	v_lshl_add_u32 v248, v243, 4, v248
	v_add_u32_e32 v249, s19, v250
	v_lshlrev_b32_e32 v249, 11, v249
	v_lshl_add_u32 v249, v243, 4, v249
	v_add_u32_e32 v251, s5, v250
	v_lshlrev_b32_e32 v251, 12, v251
	v_lshl_add_u32 v243, v243, 5, v251
	v_and_b32_e32 v251, 63, v0
	v_and_b32_e32 v250, 15, v251
	v_lshrrev_b32_e32 v251, 4, v251
	v_lshl_add_u32 v250, v250, 2, v251
	v_lshlrev_b32_e32 v250, 2, v250
	v_mov_b32_e32 v22, 0
	global_load_dwordx4 v[24:27], v243, s[12:13]
	global_load_dwordx4 v[28:31], v243, s[12:13] offset:16
	global_load_dwordx4 v[32:35], v246, s[14:15]
	global_load_dwordx4 v[36:39], v247, s[14:15]
	global_load_dwordx4 v[40:43], v248, s[14:15]
	global_load_dwordx4 v[44:47], v249, s[14:15]
	global_load_dwordx4 v[48:51], v243, s[12:13] offset:128
	global_load_dwordx4 v[52:55], v243, s[12:13] offset:144
	global_load_dwordx4 v[56:59], v246, s[14:15] offset:64
	global_load_dwordx4 v[60:63], v247, s[14:15] offset:64
	global_load_dwordx4 v[64:67], v248, s[14:15] offset:64
	global_load_dwordx4 v[80:83], v249, s[14:15] offset:64
	global_load_dwordx4 v[84:87], v243, s[12:13] offset:256
	global_load_dwordx4 v[88:91], v243, s[12:13] offset:272
	global_load_dwordx4 v[92:95], v246, s[14:15] offset:128
	global_load_dwordx4 v[96:99], v247, s[14:15] offset:128
	global_load_dwordx4 v[100:103], v248, s[14:15] offset:128
	global_load_dwordx4 v[104:107], v249, s[14:15] offset:128
	global_load_dwordx4 v[108:111], v243, s[12:13] offset:384
	global_load_dwordx4 v[112:115], v243, s[12:13] offset:400
	global_load_dwordx4 v[116:119], v246, s[14:15] offset:192
	global_load_dwordx4 v[120:123], v247, s[14:15] offset:192
	global_load_dwordx4 v[124:127], v248, s[14:15] offset:192
	global_load_dwordx4 v[128:131], v249, s[14:15] offset:192
	global_load_dwordx4 v[132:135], v243, s[12:13] offset:512
	global_load_dwordx4 v[136:139], v243, s[12:13] offset:528
	global_load_dwordx4 v[140:143], v246, s[14:15] offset:256
	global_load_dwordx4 v[144:147], v247, s[14:15] offset:256
	global_load_dwordx4 v[148:151], v248, s[14:15] offset:256
	global_load_dwordx4 v[152:155], v249, s[14:15] offset:256
	s_waitcnt vmcnt(24)
	ds_bpermute_b32 v172, v250, v24
	ds_bpermute_b32 v173, v250, v25
	ds_bpermute_b32 v174, v250, v26
	ds_bpermute_b32 v175, v250, v27
	ds_bpermute_b32 v176, v250, v28
	ds_bpermute_b32 v177, v250, v29
	ds_bpermute_b32 v178, v250, v30
	ds_bpermute_b32 v179, v250, v31
	ds_bpermute_b32 v180, v250, v32
	ds_bpermute_b32 v181, v250, v33
	ds_bpermute_b32 v182, v250, v34
	ds_bpermute_b32 v183, v250, v35
	ds_bpermute_b32 v184, v250, v36
	ds_bpermute_b32 v185, v250, v37
	ds_bpermute_b32 v186, v250, v38
	ds_bpermute_b32 v187, v250, v39
	ds_bpermute_b32 v188, v250, v40
	ds_bpermute_b32 v189, v250, v41
	ds_bpermute_b32 v190, v250, v42
	ds_bpermute_b32 v191, v250, v43
	ds_bpermute_b32 v202, v250, v44
	ds_bpermute_b32 v203, v250, v45
	ds_bpermute_b32 v204, v250, v46
	ds_bpermute_b32 v205, v250, v47
	global_load_dwordx4 v[24:27], v243, s[12:13] offset:640
	global_load_dwordx4 v[28:31], v243, s[12:13] offset:656
	global_load_dwordx4 v[32:35], v246, s[14:15] offset:320
	global_load_dwordx4 v[36:39], v247, s[14:15] offset:320
	global_load_dwordx4 v[40:43], v248, s[14:15] offset:320
	global_load_dwordx4 v[44:47], v249, s[14:15] offset:320
	s_waitcnt lgkmcnt(15)
	v_fmac_f32_e32 v22, v172, v172
	v_fmac_f32_e32 v22, v173, v173
	v_fmac_f32_e32 v22, v174, v174
	v_fmac_f32_e32 v22, v175, v175
	v_fmac_f32_e32 v22, v176, v176
	v_fmac_f32_e32 v22, v177, v177
	v_fmac_f32_e32 v22, v178, v178
	v_fmac_f32_e32 v22, v179, v179
	v_cvt_pk_bf16_f32 v172, v172, v173
	v_cvt_pk_bf16_f32 v173, v174, v175
	v_cvt_pk_bf16_f32 v174, v176, v177
	v_cvt_pk_bf16_f32 v175, v178, v179
	s_waitcnt vmcnt(24)
	ds_bpermute_b32 v206, v250, v48
	ds_bpermute_b32 v207, v250, v49
	ds_bpermute_b32 v208, v250, v50
	ds_bpermute_b32 v209, v250, v51
	ds_bpermute_b32 v210, v250, v52
	ds_bpermute_b32 v211, v250, v53
	ds_bpermute_b32 v212, v250, v54
	ds_bpermute_b32 v213, v250, v55
	s_waitcnt lgkmcnt(15)
	v_mfma_f32_16x16x32_bf16 v[2:5], v[172:175], v[180:183], 0
	ds_bpermute_b32 v214, v250, v56
	ds_bpermute_b32 v215, v250, v57
	ds_bpermute_b32 v216, v250, v58
	ds_bpermute_b32 v217, v250, v59
	s_waitcnt lgkmcnt(15)
	v_mfma_f32_16x16x32_bf16 v[14:17], v[172:175], v[184:187], 0
	ds_bpermute_b32 v218, v250, v60
	ds_bpermute_b32 v219, v250, v61
	ds_bpermute_b32 v220, v250, v62
	ds_bpermute_b32 v221, v250, v63
	s_waitcnt lgkmcnt(15)
	v_mfma_f32_16x16x32_bf16 v[18:21], v[172:175], v[188:191], 0
	ds_bpermute_b32 v222, v250, v64
	ds_bpermute_b32 v223, v250, v65
	ds_bpermute_b32 v224, v250, v66
	ds_bpermute_b32 v225, v250, v67
	s_waitcnt lgkmcnt(15)
	v_mfma_f32_16x16x32_bf16 v[6:9], v[172:175], v[202:205], 0
	ds_bpermute_b32 v226, v250, v80
	ds_bpermute_b32 v227, v250, v81
	ds_bpermute_b32 v228, v250, v82
	ds_bpermute_b32 v229, v250, v83
	global_load_dwordx4 v[48:51], v243, s[12:13] offset:768
	global_load_dwordx4 v[52:55], v243, s[12:13] offset:784
	global_load_dwordx4 v[56:59], v246, s[14:15] offset:384
	global_load_dwordx4 v[60:63], v247, s[14:15] offset:384
	global_load_dwordx4 v[64:67], v248, s[14:15] offset:384
	global_load_dwordx4 v[80:83], v249, s[14:15] offset:384
	s_waitcnt lgkmcnt(15)
	v_fmac_f32_e32 v22, v206, v206
	v_fmac_f32_e32 v22, v207, v207
	v_fmac_f32_e32 v22, v208, v208
	v_fmac_f32_e32 v22, v209, v209
	v_fmac_f32_e32 v22, v210, v210
	v_fmac_f32_e32 v22, v211, v211
	v_fmac_f32_e32 v22, v212, v212
	v_fmac_f32_e32 v22, v213, v213
	v_cvt_pk_bf16_f32 v206, v206, v207
	v_cvt_pk_bf16_f32 v207, v208, v209
	v_cvt_pk_bf16_f32 v208, v210, v211
	v_cvt_pk_bf16_f32 v209, v212, v213
	s_waitcnt vmcnt(24)
	ds_bpermute_b32 v172, v250, v84
	ds_bpermute_b32 v173, v250, v85
	ds_bpermute_b32 v174, v250, v86
	ds_bpermute_b32 v175, v250, v87
	ds_bpermute_b32 v176, v250, v88
	ds_bpermute_b32 v177, v250, v89
	ds_bpermute_b32 v178, v250, v90
	ds_bpermute_b32 v179, v250, v91
	s_waitcnt lgkmcnt(15)
	v_mfma_f32_16x16x32_bf16 v[2:5], v[206:209], v[214:217], v[2:5]
	ds_bpermute_b32 v180, v250, v92
	ds_bpermute_b32 v181, v250, v93
	ds_bpermute_b32 v182, v250, v94
	ds_bpermute_b32 v183, v250, v95
	s_waitcnt lgkmcnt(15)
	v_mfma_f32_16x16x32_bf16 v[14:17], v[206:209], v[218:221], v[14:17]
	ds_bpermute_b32 v184, v250, v96
	ds_bpermute_b32 v185, v250, v97
	ds_bpermute_b32 v186, v250, v98
	ds_bpermute_b32 v187, v250, v99
	s_waitcnt lgkmcnt(15)
	v_mfma_f32_16x16x32_bf16 v[18:21], v[206:209], v[222:225], v[18:21]
	ds_bpermute_b32 v188, v250, v100
	ds_bpermute_b32 v189, v250, v101
	ds_bpermute_b32 v190, v250, v102
	ds_bpermute_b32 v191, v250, v103
	s_waitcnt lgkmcnt(15)
	v_mfma_f32_16x16x32_bf16 v[6:9], v[206:209], v[226:229], v[6:9]
	ds_bpermute_b32 v202, v250, v104
	ds_bpermute_b32 v203, v250, v105
	ds_bpermute_b32 v204, v250, v106
	ds_bpermute_b32 v205, v250, v107
	global_load_dwordx4 v[84:87], v243, s[12:13] offset:896
	global_load_dwordx4 v[88:91], v243, s[12:13] offset:912
	global_load_dwordx4 v[92:95], v246, s[14:15] offset:448
	global_load_dwordx4 v[96:99], v247, s[14:15] offset:448
	global_load_dwordx4 v[100:103], v248, s[14:15] offset:448
	global_load_dwordx4 v[104:107], v249, s[14:15] offset:448
	s_waitcnt lgkmcnt(15)
	v_fmac_f32_e32 v22, v172, v172
	v_fmac_f32_e32 v22, v173, v173
	v_fmac_f32_e32 v22, v174, v174
	v_fmac_f32_e32 v22, v175, v175
	v_fmac_f32_e32 v22, v176, v176
	v_fmac_f32_e32 v22, v177, v177
	v_fmac_f32_e32 v22, v178, v178
	v_fmac_f32_e32 v22, v179, v179
	v_cvt_pk_bf16_f32 v172, v172, v173
	v_cvt_pk_bf16_f32 v173, v174, v175
	v_cvt_pk_bf16_f32 v174, v176, v177
	v_cvt_pk_bf16_f32 v175, v178, v179
	s_waitcnt vmcnt(24)
	ds_bpermute_b32 v206, v250, v108
	ds_bpermute_b32 v207, v250, v109
	ds_bpermute_b32 v208, v250, v110
	ds_bpermute_b32 v209, v250, v111
	ds_bpermute_b32 v210, v250, v112
	ds_bpermute_b32 v211, v250, v113
	ds_bpermute_b32 v212, v250, v114
	ds_bpermute_b32 v213, v250, v115
	s_waitcnt lgkmcnt(15)
	v_mfma_f32_16x16x32_bf16 v[2:5], v[172:175], v[180:183], v[2:5]
	ds_bpermute_b32 v214, v250, v116
	ds_bpermute_b32 v215, v250, v117
	ds_bpermute_b32 v216, v250, v118
	ds_bpermute_b32 v217, v250, v119
	s_waitcnt lgkmcnt(15)
	v_mfma_f32_16x16x32_bf16 v[14:17], v[172:175], v[184:187], v[14:17]
	ds_bpermute_b32 v218, v250, v120
	ds_bpermute_b32 v219, v250, v121
	ds_bpermute_b32 v220, v250, v122
	ds_bpermute_b32 v221, v250, v123
	s_waitcnt lgkmcnt(15)
	v_mfma_f32_16x16x32_bf16 v[18:21], v[172:175], v[188:191], v[18:21]
	ds_bpermute_b32 v222, v250, v124
	ds_bpermute_b32 v223, v250, v125
	ds_bpermute_b32 v224, v250, v126
	ds_bpermute_b32 v225, v250, v127
	s_waitcnt lgkmcnt(15)
	v_mfma_f32_16x16x32_bf16 v[6:9], v[172:175], v[202:205], v[6:9]
	ds_bpermute_b32 v226, v250, v128
	ds_bpermute_b32 v227, v250, v129
	ds_bpermute_b32 v228, v250, v130
	ds_bpermute_b32 v229, v250, v131
	s_waitcnt lgkmcnt(15)
	v_fmac_f32_e32 v22, v206, v206
	v_fmac_f32_e32 v22, v207, v207
	v_fmac_f32_e32 v22, v208, v208
	v_fmac_f32_e32 v22, v209, v209
	v_fmac_f32_e32 v22, v210, v210
	v_fmac_f32_e32 v22, v211, v211
	v_fmac_f32_e32 v22, v212, v212
	v_fmac_f32_e32 v22, v213, v213
	v_cvt_pk_bf16_f32 v206, v206, v207
	v_cvt_pk_bf16_f32 v207, v208, v209
	v_cvt_pk_bf16_f32 v208, v210, v211
	v_cvt_pk_bf16_f32 v209, v212, v213
	s_waitcnt vmcnt(18)
	ds_bpermute_b32 v172, v250, v132
	ds_bpermute_b32 v173, v250, v133
	ds_bpermute_b32 v174, v250, v134
	ds_bpermute_b32 v175, v250, v135
	ds_bpermute_b32 v176, v250, v136
	ds_bpermute_b32 v177, v250, v137
	ds_bpermute_b32 v178, v250, v138
	ds_bpermute_b32 v179, v250, v139
	s_waitcnt lgkmcnt(15)
	v_mfma_f32_16x16x32_bf16 v[2:5], v[206:209], v[214:217], v[2:5]
	ds_bpermute_b32 v180, v250, v140
	ds_bpermute_b32 v181, v250, v141
	ds_bpermute_b32 v182, v250, v142
	ds_bpermute_b32 v183, v250, v143
	s_waitcnt lgkmcnt(15)
	v_mfma_f32_16x16x32_bf16 v[14:17], v[206:209], v[218:221], v[14:17]
	ds_bpermute_b32 v184, v250, v144
	ds_bpermute_b32 v185, v250, v145
	ds_bpermute_b32 v186, v250, v146
	ds_bpermute_b32 v187, v250, v147
	s_waitcnt lgkmcnt(15)
	v_mfma_f32_16x16x32_bf16 v[18:21], v[206:209], v[222:225], v[18:21]
	ds_bpermute_b32 v188, v250, v148
	ds_bpermute_b32 v189, v250, v149
	ds_bpermute_b32 v190, v250, v150
	ds_bpermute_b32 v191, v250, v151
	s_waitcnt lgkmcnt(15)
	v_mfma_f32_16x16x32_bf16 v[6:9], v[206:209], v[226:229], v[6:9]
	ds_bpermute_b32 v202, v250, v152
	ds_bpermute_b32 v203, v250, v153
	ds_bpermute_b32 v204, v250, v154
	ds_bpermute_b32 v205, v250, v155
	s_waitcnt lgkmcnt(15)
	v_fmac_f32_e32 v22, v172, v172
	v_fmac_f32_e32 v22, v173, v173
	v_fmac_f32_e32 v22, v174, v174
	v_fmac_f32_e32 v22, v175, v175
	v_fmac_f32_e32 v22, v176, v176
	v_fmac_f32_e32 v22, v177, v177
	v_fmac_f32_e32 v22, v178, v178
	v_fmac_f32_e32 v22, v179, v179
	v_cvt_pk_bf16_f32 v172, v172, v173
	v_cvt_pk_bf16_f32 v173, v174, v175
	v_cvt_pk_bf16_f32 v174, v176, v177
	v_cvt_pk_bf16_f32 v175, v178, v179
	s_waitcnt vmcnt(12)
	ds_bpermute_b32 v206, v250, v24
	ds_bpermute_b32 v207, v250, v25
	ds_bpermute_b32 v208, v250, v26
	ds_bpermute_b32 v209, v250, v27
	ds_bpermute_b32 v210, v250, v28
	ds_bpermute_b32 v211, v250, v29
	ds_bpermute_b32 v212, v250, v30
	ds_bpermute_b32 v213, v250, v31
	s_waitcnt lgkmcnt(15)
	v_mfma_f32_16x16x32_bf16 v[2:5], v[172:175], v[180:183], v[2:5]
	ds_bpermute_b32 v214, v250, v32
	ds_bpermute_b32 v215, v250, v33
	ds_bpermute_b32 v216, v250, v34
	ds_bpermute_b32 v217, v250, v35
	s_waitcnt lgkmcnt(15)
	v_mfma_f32_16x16x32_bf16 v[14:17], v[172:175], v[184:187], v[14:17]
	ds_bpermute_b32 v218, v250, v36
	ds_bpermute_b32 v219, v250, v37
	ds_bpermute_b32 v220, v250, v38
	ds_bpermute_b32 v221, v250, v39
	s_waitcnt lgkmcnt(15)
	v_mfma_f32_16x16x32_bf16 v[18:21], v[172:175], v[188:191], v[18:21]
	ds_bpermute_b32 v222, v250, v40
	ds_bpermute_b32 v223, v250, v41
	ds_bpermute_b32 v224, v250, v42
	ds_bpermute_b32 v225, v250, v43
	s_waitcnt lgkmcnt(15)
	v_mfma_f32_16x16x32_bf16 v[6:9], v[172:175], v[202:205], v[6:9]
	ds_bpermute_b32 v226, v250, v44
	ds_bpermute_b32 v227, v250, v45
	ds_bpermute_b32 v228, v250, v46
	ds_bpermute_b32 v229, v250, v47
	s_waitcnt lgkmcnt(15)
	v_fmac_f32_e32 v22, v206, v206
	v_fmac_f32_e32 v22, v207, v207
	v_fmac_f32_e32 v22, v208, v208
	v_fmac_f32_e32 v22, v209, v209
	v_fmac_f32_e32 v22, v210, v210
	v_fmac_f32_e32 v22, v211, v211
	v_fmac_f32_e32 v22, v212, v212
	v_fmac_f32_e32 v22, v213, v213
	v_cvt_pk_bf16_f32 v206, v206, v207
	v_cvt_pk_bf16_f32 v207, v208, v209
	v_cvt_pk_bf16_f32 v208, v210, v211
	v_cvt_pk_bf16_f32 v209, v212, v213
	s_waitcnt vmcnt(6)
	ds_bpermute_b32 v172, v250, v48
	ds_bpermute_b32 v173, v250, v49
	ds_bpermute_b32 v174, v250, v50
	ds_bpermute_b32 v175, v250, v51
	ds_bpermute_b32 v176, v250, v52
	ds_bpermute_b32 v177, v250, v53
	ds_bpermute_b32 v178, v250, v54
	ds_bpermute_b32 v179, v250, v55
	s_waitcnt lgkmcnt(15)
	v_mfma_f32_16x16x32_bf16 v[2:5], v[206:209], v[214:217], v[2:5]
	ds_bpermute_b32 v180, v250, v56
	ds_bpermute_b32 v181, v250, v57
	ds_bpermute_b32 v182, v250, v58
	ds_bpermute_b32 v183, v250, v59
	s_waitcnt lgkmcnt(15)
	v_mfma_f32_16x16x32_bf16 v[14:17], v[206:209], v[218:221], v[14:17]
	ds_bpermute_b32 v184, v250, v60
	ds_bpermute_b32 v185, v250, v61
	ds_bpermute_b32 v186, v250, v62
	ds_bpermute_b32 v187, v250, v63
	s_waitcnt lgkmcnt(15)
	v_mfma_f32_16x16x32_bf16 v[18:21], v[206:209], v[222:225], v[18:21]
	ds_bpermute_b32 v188, v250, v64
	ds_bpermute_b32 v189, v250, v65
	ds_bpermute_b32 v190, v250, v66
	ds_bpermute_b32 v191, v250, v67
	s_waitcnt lgkmcnt(15)
	v_mfma_f32_16x16x32_bf16 v[6:9], v[206:209], v[226:229], v[6:9]
	ds_bpermute_b32 v202, v250, v80
	ds_bpermute_b32 v203, v250, v81
	ds_bpermute_b32 v204, v250, v82
	ds_bpermute_b32 v205, v250, v83
	s_waitcnt lgkmcnt(15)
	v_fmac_f32_e32 v22, v172, v172
	v_fmac_f32_e32 v22, v173, v173
	v_fmac_f32_e32 v22, v174, v174
	v_fmac_f32_e32 v22, v175, v175
	v_fmac_f32_e32 v22, v176, v176
	v_fmac_f32_e32 v22, v177, v177
	v_fmac_f32_e32 v22, v178, v178
	v_fmac_f32_e32 v22, v179, v179
	v_cvt_pk_bf16_f32 v172, v172, v173
	v_cvt_pk_bf16_f32 v173, v174, v175
	v_cvt_pk_bf16_f32 v174, v176, v177
	v_cvt_pk_bf16_f32 v175, v178, v179
	s_waitcnt vmcnt(0)
	ds_bpermute_b32 v206, v250, v84
	ds_bpermute_b32 v207, v250, v85
	ds_bpermute_b32 v208, v250, v86
	ds_bpermute_b32 v209, v250, v87
	ds_bpermute_b32 v210, v250, v88
	ds_bpermute_b32 v211, v250, v89
	ds_bpermute_b32 v212, v250, v90
	ds_bpermute_b32 v213, v250, v91
	s_waitcnt lgkmcnt(15)
	v_mfma_f32_16x16x32_bf16 v[2:5], v[172:175], v[180:183], v[2:5]
	ds_bpermute_b32 v214, v250, v92
	ds_bpermute_b32 v215, v250, v93
	ds_bpermute_b32 v216, v250, v94
	ds_bpermute_b32 v217, v250, v95
	s_waitcnt lgkmcnt(15)
	v_mfma_f32_16x16x32_bf16 v[14:17], v[172:175], v[184:187], v[14:17]
	ds_bpermute_b32 v218, v250, v96
	ds_bpermute_b32 v219, v250, v97
	ds_bpermute_b32 v220, v250, v98
	ds_bpermute_b32 v221, v250, v99
	s_waitcnt lgkmcnt(15)
	v_mfma_f32_16x16x32_bf16 v[18:21], v[172:175], v[188:191], v[18:21]
	ds_bpermute_b32 v222, v250, v100
	ds_bpermute_b32 v223, v250, v101
	ds_bpermute_b32 v224, v250, v102
	ds_bpermute_b32 v225, v250, v103
	s_waitcnt lgkmcnt(15)
	v_mfma_f32_16x16x32_bf16 v[6:9], v[172:175], v[202:205], v[6:9]
	ds_bpermute_b32 v226, v250, v104
	ds_bpermute_b32 v227, v250, v105
	ds_bpermute_b32 v228, v250, v106
	ds_bpermute_b32 v229, v250, v107
	s_waitcnt lgkmcnt(15)
	v_fmac_f32_e32 v22, v206, v206
	v_fmac_f32_e32 v22, v207, v207
	v_fmac_f32_e32 v22, v208, v208
	v_fmac_f32_e32 v22, v209, v209
	v_fmac_f32_e32 v22, v210, v210
	v_fmac_f32_e32 v22, v211, v211
	v_fmac_f32_e32 v22, v212, v212
	v_fmac_f32_e32 v22, v213, v213
	v_cvt_pk_bf16_f32 v206, v206, v207
	v_cvt_pk_bf16_f32 v207, v208, v209
	v_cvt_pk_bf16_f32 v208, v210, v211
	v_cvt_pk_bf16_f32 v209, v212, v213
	s_nop 1
	s_waitcnt lgkmcnt(12)
	v_mfma_f32_16x16x32_bf16 v[2:5], v[206:209], v[214:217], v[2:5]
	s_waitcnt lgkmcnt(8)
	v_mfma_f32_16x16x32_bf16 v[14:17], v[206:209], v[218:221], v[14:17]
	s_waitcnt lgkmcnt(4)
	v_mfma_f32_16x16x32_bf16 v[18:21], v[206:209], v[222:225], v[18:21]
	s_waitcnt lgkmcnt(0)
	v_mfma_f32_16x16x32_bf16 v[6:9], v[206:209], v[226:229], v[6:9]
	v_and_b32_e32 v252, 63, v0
	v_xor_b32_e32 v254, 32, v252
	v_xor_b32_e32 v252, 16, v252
	v_lshlrev_b32_e32 v252, 2, v252
	v_lshlrev_b32_e32 v254, 2, v254
	ds_bpermute_b32 v251, v252, v22
	s_waitcnt lgkmcnt(0)
	v_add_f32_e32 v22, v22, v251
	ds_bpermute_b32 v251, v254, v22
	s_waitcnt lgkmcnt(0)
	v_add_f32_e32 v22, v22, v251
	v_mov_b32_e32 v23, 0
	s_barrier
	s_nop 7
	ds_write_b128 v79, v[2:5]
	ds_write_b128 v79, v[14:17] offset:1024
	ds_write_b128 v79, v[18:21] offset:2048
	s_nop 4
	ds_write_b128 v79, v[6:9] offset:3072
	v_add_u32_e32 v2, s8, v76
	s_andn2_b64 vcc, exec, s[0:1]
	s_waitcnt lgkmcnt(4)
	v_add_f32_e32 v10, v22, v23
	ds_write_b32 v2, v10 offset:32768
	s_waitcnt lgkmcnt(0)
	s_barrier
	s_cbranch_vccnz .LBB0_1051
	ds_read_b128 v[4:7], v79
	ds_read_b128 v[8:11], v79 offset:8192
	ds_read_b128 v[12:15], v79 offset:16384
	ds_read_b128 v[16:19], v79 offset:24576
	ds_read_b128 v[20:23], v79 offset:1024
	ds_read_b128 v[24:27], v79 offset:9216
	s_waitcnt lgkmcnt(4)
	v_pk_add_f32 v[28:29], v[6:7], v[10:11]
	v_pk_add_f32 v[30:31], v[4:5], v[8:9]
	ds_read_b128 v[4:7], v79 offset:17408
	ds_read_b128 v[8:11], v79 offset:25600
	s_waitcnt lgkmcnt(4)
	v_pk_add_f32 v[14:15], v[14:15], v[18:19]
	v_pk_add_f32 v[12:13], v[12:13], v[16:17]
	v_pk_add_f32 v[28:29], v[28:29], v[14:15]
	v_pk_add_f32 v[30:31], v[30:31], v[12:13]
	s_waitcnt lgkmcnt(2)
	v_pk_add_f32 v[12:13], v[22:23], v[26:27]
	v_pk_add_f32 v[14:15], v[20:21], v[24:25]
	s_waitcnt lgkmcnt(0)
	v_pk_add_f32 v[6:7], v[6:7], v[10:11]
	v_pk_add_f32 v[4:5], v[4:5], v[8:9]
	v_pk_add_f32 v[32:33], v[12:13], v[6:7]
	v_pk_add_f32 v[34:35], v[14:15], v[4:5]
	ds_read_b128 v[4:7], v79 offset:2048
	ds_read_b128 v[8:11], v79 offset:10240
	ds_read_b128 v[12:15], v79 offset:18432
	ds_read_b128 v[16:19], v79 offset:26624
	ds_read_b128 v[20:23], v79 offset:3072
	ds_read_b128 v[24:27], v79 offset:11264
	s_waitcnt lgkmcnt(4)
	v_pk_add_f32 v[36:37], v[6:7], v[10:11]
	v_pk_add_f32 v[38:39], v[4:5], v[8:9]
	ds_read_b128 v[4:7], v79 offset:19456
	ds_read_b128 v[8:11], v79 offset:27648
	s_waitcnt lgkmcnt(4)
	v_pk_add_f32 v[12:13], v[12:13], v[16:17]
	ds_read2st64_b32 v[16:17], v2 offset0:128 offset1:130
	ds_read2st64_b32 v[2:3], v2 offset0:132 offset1:134
	v_pk_add_f32 v[14:15], v[14:15], v[18:19]
	s_waitcnt lgkmcnt(4)
	v_pk_add_f32 v[18:19], v[22:23], v[26:27]
	s_waitcnt lgkmcnt(2)
	v_pk_add_f32 v[6:7], v[6:7], v[10:11]
	s_waitcnt lgkmcnt(1)
	v_mov_b32_e32 v10, v16
	s_waitcnt lgkmcnt(0)
	v_mov_b32_e32 v11, v2
	v_mov_b32_e32 v2, v17
	v_pk_add_f32 v[2:3], v[10:11], v[2:3]
	v_pk_add_f32 v[20:21], v[20:21], v[24:25]
	v_add_f32_e32 v2, v2, v3
	v_fmamk_f32 v2, v2, 0x3a800000, v235
	v_mul_f32_e32 v3, 0x4b800000, v2
	v_cmp_gt_f32_e32 vcc, s41, v2
	v_pk_add_f32 v[12:13], v[38:39], v[12:13]
	v_pk_add_f32 v[14:15], v[36:37], v[14:15]
	v_cndmask_b32_e32 v2, v2, v3, vcc
	v_rsq_f32_e32 v10, v2
	v_pk_add_f32 v[2:3], v[4:5], v[8:9]
	v_pk_add_f32 v[4:5], v[18:19], v[6:7]
	v_and_or_b32 v7, v1, 64, v78
	v_mul_f32_e32 v6, 0x45800000, v10
	v_cndmask_b32_e32 v6, v10, v6, vcc
	v_lshlrev_b32_e32 v7, 2, v7
	ds_bpermute_b32 v8, v7, v6
	v_or_b32_e32 v9, s5, v78
	v_lshlrev_b32_e32 v194, 13, v9
	ds_bpermute_b32 v10, v7, v6 offset:4
	ds_bpermute_b32 v11, v7, v6 offset:8
	s_waitcnt lgkmcnt(2)
	v_mul_f32_e32 v9, v30, v8
	v_or_b32_e32 v7, 12, v7
	s_ashr_i32 s5, s4, 31
	v_max_f32_e32 v9, 0, v9
	ds_bpermute_b32 v16, v7, v6
	v_lshl_add_u64 v[6:7], s[4:5], 1, v[72:73]
	v_mul_f32_e32 v9, v9, v9
	v_lshl_add_u64 v[6:7], v[6:7], 0, v[194:195]
	v_cvt_pk_bf16_f32 v9, v9, v195
	global_store_short v[6:7], v9, off
	v_mul_f32_e32 v9, v34, v8
	v_max_f32_e32 v9, 0, v9
	v_mul_f32_e32 v9, v9, v9
	v_pk_add_f32 v[2:3], v[20:21], v[2:3]
	v_cvt_pk_bf16_f32 v9, v9, v195
	global_store_short v[6:7], v9, off offset:32
	v_mul_f32_e32 v9, v12, v8
	v_mul_f32_e32 v2, v2, v8
	v_max_f32_e32 v9, 0, v9
	v_max_f32_e32 v2, 0, v2
	v_mul_f32_e32 v9, v9, v9
	v_mul_f32_e32 v2, v2, v2
	v_cvt_pk_bf16_f32 v9, v9, v195
	global_store_short v[6:7], v9, off offset:64
	v_cvt_pk_bf16_f32 v2, v2, v195
	global_store_short v[6:7], v2, off offset:96
	s_waitcnt lgkmcnt(2)
	v_mul_f32_e32 v2, v31, v10
	v_max_f32_e32 v2, 0, v2
	s_movk_i32 s4, 0x2000
	v_mul_f32_e32 v2, v2, v2
	v_add_co_u32_e32 v8, vcc, s4, v6
	v_cvt_pk_bf16_f32 v2, v2, v195
	s_movk_i32 s4, 0x4000
	s_nop 0
	v_addc_co_u32_e32 v9, vcc, 0, v7, vcc
	global_store_short v[8:9], v2, off
	v_mul_f32_e32 v2, v35, v10
	v_max_f32_e32 v2, 0, v2
	v_mul_f32_e32 v2, v2, v2
	v_cvt_pk_bf16_f32 v2, v2, v195
	global_store_short v[8:9], v2, off offset:32
	v_mul_f32_e32 v2, v13, v10
	v_max_f32_e32 v2, 0, v2
	v_mul_f32_e32 v2, v2, v2
	v_cvt_pk_bf16_f32 v2, v2, v195
	global_store_short v[8:9], v2, off offset:64
	v_mul_f32_e32 v2, v3, v10
	v_max_f32_e32 v2, 0, v2
	v_mul_f32_e32 v2, v2, v2
	v_cvt_pk_bf16_f32 v2, v2, v195
	global_store_short v[8:9], v2, off offset:96
	s_waitcnt lgkmcnt(1)
	v_mul_f32_e32 v2, v28, v11
	v_max_f32_e32 v2, 0, v2
	v_mul_f32_e32 v2, v2, v2
	v_cvt_pk_bf16_f32 v8, v2, v195
	v_add_co_u32_e32 v2, vcc, s4, v6
	v_mul_f32_e32 v4, v4, v11
	s_nop 0
	v_addc_co_u32_e32 v3, vcc, 0, v7, vcc
	global_store_short v[2:3], v8, off
	v_mul_f32_e32 v8, v32, v11
	v_max_f32_e32 v8, 0, v8
	v_mul_f32_e32 v8, v8, v8
	v_cvt_pk_bf16_f32 v8, v8, v195
	global_store_short v[2:3], v8, off offset:32
	v_mul_f32_e32 v8, v14, v11
	v_max_f32_e32 v8, 0, v8
	v_max_f32_e32 v4, 0, v4
	v_mul_f32_e32 v8, v8, v8
	v_mul_f32_e32 v4, v4, v4
	v_cvt_pk_bf16_f32 v8, v8, v195
	global_store_short v[2:3], v8, off offset:64
	v_cvt_pk_bf16_f32 v4, v4, v195
	global_store_short v[2:3], v4, off offset:96
	s_waitcnt lgkmcnt(0)
	v_mul_f32_e32 v2, v29, v16
	v_max_f32_e32 v2, 0, v2
	v_mul_f32_e32 v2, v2, v2
	s_movk_i32 s4, 0x6000
	v_cvt_pk_bf16_f32 v4, v2, v195
	v_add_co_u32_e32 v2, vcc, s4, v6
	s_nop 1
	v_addc_co_u32_e32 v3, vcc, 0, v7, vcc
	global_store_short v[2:3], v4, off
	v_mul_f32_e32 v4, v33, v16
	v_max_f32_e32 v4, 0, v4
	v_mul_f32_e32 v4, v4, v4
	v_cvt_pk_bf16_f32 v4, v4, v195
	global_store_short v[2:3], v4, off offset:32
	v_mul_f32_e32 v4, v15, v16
	v_max_f32_e32 v4, 0, v4
	v_mul_f32_e32 v4, v4, v4
	v_cvt_pk_bf16_f32 v4, v4, v195
	global_store_short v[2:3], v4, off offset:64
	v_mul_f32_e32 v4, v5, v16
	v_max_f32_e32 v4, 0, v4
	v_mul_f32_e32 v4, v4, v4
	v_cvt_pk_bf16_f32 v4, v4, v195
	global_store_short v[2:3], v4, off offset:96
	s_branch .LBB0_1051
